# in-proj GEMM k-loop rewritten like out-proj (fragment ping-pong, 1 barrier per k-step, next-tile prefetch), staging kept clear of epilogue scratch
# speedup vs baseline: 1.1003x; 1.0367x over previous
.LBB0_180:
	s_or_b64 exec, exec, s[0:1]
	v_readlane_b32 s0, v252, 1
	v_readlane_b32 s1, v252, 2
	s_mov_b32 s17, s23
	v_mov_b32_e32 v4, v222
	s_lshl_b32 s8, s16, 9
	s_andn2_b64 vcc, exec, s[0:1]
	s_mov_b32 s9, s23
	s_waitcnt lgkmcnt(0)
	s_barrier
	s_cbranch_vccnz .LBB0_488
	v_lshlrev_b32_e32 v2, 3, v4
	v_ashrrev_i32_e32 v6, 3, v4
	v_and_b32_e32 v2, 56, v2
	v_lshl_or_b32 v2, v6, 10, v2
	v_lshlrev_b32_e32 v7, 7, v6
	v_xor_b32_e32 v6, v6, v4
	v_lshlrev_b32_e32 v6, 4, v6
	s_mul_i32 s1, s16, 0x700000
	v_readlane_b32 s4, v253, 62
	v_and_b32_e32 v6, 0x70, v6
	s_mul_hi_u32 s0, s16, 0x700000
	s_add_u32 s66, s4, s1
	v_readlane_b32 s1, v253, 63
	v_add3_u32 v174, 32, v7, v6
	v_lshlrev_b32_e32 v6, 7, v4
	s_addc_u32 s67, s1, s0
	s_lshl_b64 s[0:1], s[8:9], 2
	v_and_b32_e32 v6, 0x2780, v6
	s_add_u32 s38, s30, s0
	v_and_b32_e32 v0, 15, v4
	v_add_u32_e32 v24, 32, v6
	v_ashrrev_i32_e32 v6, 1, v4
	s_movk_i32 s0, 0xffc0
	v_lshrrev_b32_e32 v1, 4, v4
	v_and_or_b32 v175, v6, s0, v0
	v_and_b32_e32 v6, 7, v4
	v_bitop3_b32 v1, v1, v6, 3 bitop3:0x6c
	v_lshl_add_u32 v0, v175, 7, 32
	v_lshlrev_b32_e32 v1, 4, v1
	s_addc_u32 s39, s31, s1
	v_bfe_u32 v5, v4, 4, 2
	v_and_b32_e32 v27, 64, v4
	v_add_u32_e32 v176, v24, v1
	v_add_u32_e32 v177, v0, v1
	v_xor_b32_e32 v1, 64, v1
	v_readlane_b32 s0, v252, 6
	v_add_u32_e32 v178, v24, v1
	v_add_u32_e32 v179, v0, v1
	v_lshlrev_b32_e32 v0, 1, v27
	v_lshlrev_b32_e32 v1, 3, v5
	v_lshlrev_b32_e32 v24, 4, v5
	v_mov_b32_e32 v25, v3
	v_readlane_b32 s1, v252, 7
	v_add3_u32 v180, 32, v0, v1
	s_movk_i32 s4, 0x110
	v_lshl_add_u64 v[0:1], s[0:1], 0, v[24:25]
	v_readlane_b32 s0, v252, 4
	v_readlane_b32 s1, v252, 5
	v_ashrrev_i32_e32 v181, 4, v4
	v_add_u32_e32 v6, 0x8000, v2
	v_lshl_add_u64 v[132:133], s[0:1], 0, v[24:25]
	v_lshlrev_b32_e32 v24, 4, v4
	v_and_b32_e32 v24, 0xf0, v24
	v_add_u32_e32 v25, 0x100, v4
	v_add_u32_e32 v26, 32, v24
	v_ashrrev_i32_e32 v182, 4, v25
	v_mad_u64_u32 v[136:137], s[0:1], v182, s4, v[26:27]
	v_add_u32_e32 v25, 0x200, v4
	v_ashrrev_i32_e32 v137, 4, v25
	v_mad_u64_u32 v[138:139], s[0:1], v137, s4, v[26:27]
	v_add_u32_e32 v25, 0x300, v4
	v_ashrrev_i32_e32 v139, 4, v25
	v_mad_u64_u32 v[140:141], s[0:1], v139, s4, v[26:27]
	v_add_u32_e32 v25, 0x400, v4
	v_ashrrev_i32_e32 v141, 4, v25
	v_mad_u64_u32 v[142:143], s[0:1], v141, s4, v[26:27]
	v_add_u32_e32 v25, 0x500, v4
	v_ashrrev_i32_e32 v143, 4, v25
	v_mad_u64_u32 v[144:145], s[0:1], v143, s4, v[26:27]
	v_add_u32_e32 v25, 0x600, v4
	v_ashrrev_i32_e32 v145, 4, v25
	v_mad_u64_u32 v[146:147], s[0:1], v145, s4, v[26:27]
	v_add_u32_e32 v4, 0x700, v4
	v_ashrrev_i32_e32 v147, 4, v4
	v_mov_b32_e32 v7, v3
	v_add_u32_e32 v8, 0x10000, v2
	v_mov_b32_e32 v9, v3
	v_add_u32_e32 v10, 0x18000, v2
	v_mov_b32_e32 v11, v3
	v_add_u32_e32 v12, 0x8040, v2
	v_mov_b32_e32 v13, v3
	v_add_u32_e32 v14, 0x10040, v2
	v_mov_b32_e32 v15, v3
	v_add_u32_e32 v16, 0x18040, v2
	v_mov_b32_e32 v17, v3
	v_add_u32_e32 v18, 0x8080, v2
	v_mov_b32_e32 v19, v3
	s_waitcnt vmcnt(12)
	v_add_u32_e32 v20, 0x10080, v2
	v_mov_b32_e32 v21, v3
	v_add_u32_e32 v22, 0x18080, v2
	v_mov_b32_e32 v23, v3
	v_mad_u64_u32 v[134:135], s[0:1], v181, s4, v[26:27]
	v_mad_u64_u32 v[148:149], s[0:1], v147, s4, v[26:27]
	v_mov_b32_e32 v25, v3
	v_mul_lo_u32 v135, v175, s4
	v_lshl_add_u64 v[150:151], s[24:25], 0, v[24:25]
	v_lshl_or_b32 v149, v5, 2, v27
	v_add_u32_e32 v183, 0x18100, v2
	v_lshlrev_b64 v[152:153], 1, v[2:3]
	v_lshlrev_b64 v[154:155], 1, v[6:7]
	v_lshlrev_b64 v[156:157], 1, v[8:9]
	v_lshlrev_b64 v[158:159], 1, v[10:11]
	v_lshlrev_b64 v[160:161], 1, v[12:13]
	v_lshlrev_b64 v[162:163], 1, v[14:15]
	v_lshlrev_b64 v[164:165], 1, v[16:17]
	v_lshlrev_b64 v[166:167], 1, v[18:19]
	v_lshlrev_b64 v[168:169], 1, v[20:21]
	v_lshlrev_b64 v[170:171], 1, v[22:23]
	v_readlane_b32 s36, v252, 3
	v_lshrrev_b32_e32 v4, 3, v222
	v_and_b32_e32 v5, 7, v222
	v_lshlrev_b32_e32 v5, 4, v5
	v_lshl_or_b32 v172, v4, 11, v5
	v_add_u32_e32 v173, 0x10000, v172
	v_add_u32_e32 v183, 0x20000, v172
	v_add_u32_e32 v2, 0x30000, v172
	s_bfe_u32 s0, s36, 0xf0001
	s_mul_i32 s0, s0, 0x89af
	s_lshr_b32 s0, s0, 22
	s_mul_i32 s1, s0, 0xee
	s_sub_i32 s1, s36, s1
	s_mul_i32 s4, s1, 37
	s_lshr_b32 s5, s4, 8
	s_sub_i32 s5, s1, s5
	s_bfe_u32 s5, s5, 0x70001
	s_bfe_u32 s4, s4, 0x80008
	s_add_i32 s5, s5, s4
	s_bfe_u32 s4, s5, 0x60002
	s_mul_i32 s5, s4, 7
	s_sub_i32 s1, s1, s5
	s_and_b32 s10, s1, 0xff
	s_mul_i32 s0, s0, 7
	s_add_i32 s10, s10, s0
	v_readlane_b32 s0, v252, 8
	s_add_i32 s42, s0, s4
	s_lshl_b32 s22, s10, 7
	s_lshl_b32 s0, s10, 18
	s_add_u32 s0, s66, s0
	s_addc_u32 s1, s67, 0
	s_lshl_b32 s4, s42, 18
	s_add_u32 s4, s20, s4
	s_addc_u32 s5, s21, 0
	global_load_dwordx4 v[84:87], v172, s[0:1]
	global_load_dwordx4 v[100:103], v172, s[4:5]
	global_load_dwordx4 v[88:91], v173, s[0:1]
	global_load_dwordx4 v[104:107], v173, s[4:5]
	global_load_dwordx4 v[92:95], v183, s[0:1]
	global_load_dwordx4 v[108:111], v183, s[4:5]
	global_load_dwordx4 v[96:99], v2, s[0:1]
	global_load_dwordx4 v[112:115], v2, s[4:5]
	global_load_dwordx4 v[184:187], v172, s[0:1] offset:128
	global_load_dwordx4 v[200:203], v172, s[4:5] offset:128
	global_load_dwordx4 v[188:191], v173, s[0:1] offset:128
	global_load_dwordx4 v[204:207], v173, s[4:5] offset:128
	global_load_dwordx4 v[192:195], v183, s[0:1] offset:128
	global_load_dwordx4 v[208:211], v183, s[4:5] offset:128
	global_load_dwordx4 v[196:199], v2, s[0:1] offset:128
	global_load_dwordx4 v[212:215], v2, s[4:5] offset:128
	s_waitcnt vmcnt(8)
	s_branch .Lg0_pro

.LBB0_184:
	s_bfe_u32 s0, s36, 0xf0001
	s_mul_i32 s0, s0, 0x89af
	s_lshr_b32 s0, s0, 22
	s_mul_i32 s1, s0, 0xee
	s_sub_i32 s1, s36, s1
	s_mul_i32 s4, s1, 37
	s_lshr_b32 s5, s4, 8
	s_sub_i32 s5, s1, s5
	s_bfe_u32 s5, s5, 0x70001
	s_bfe_u32 s4, s4, 0x80008
	s_add_i32 s5, s5, s4
	s_bfe_u32 s4, s5, 0x60002
	s_mul_i32 s5, s4, 7
	s_sub_i32 s1, s1, s5
	s_and_b32 s10, s1, 0xff
	s_mul_i32 s0, s0, 7
	s_add_i32 s10, s10, s0
	v_readlane_b32 s0, v252, 8
	s_lshl_b32 s22, s10, 7
	s_add_i32 s42, s0, s4
	s_lshl_b32 s0, s10, 18
	s_add_u32 s0, s66, s0
	s_addc_u32 s1, s67, 0
	s_lshl_b32 s4, s42, 18
	s_add_u32 s4, s20, s4
	s_addc_u32 s5, s21, 0
	v_add_u32_e32 v2, 0x30000, v172
	s_waitcnt vmcnt(16)
.Lg0_pro:
	ds_write_b128 v174, v[84:87]
	ds_write_b128 v174, v[100:103] offset:32768
	ds_write_b128 v174, v[88:91] offset:4096
	ds_write_b128 v174, v[104:107] offset:36864
	ds_write_b128 v174, v[92:95] offset:8192
	ds_write_b128 v174, v[108:111] offset:40960
	ds_write_b128 v174, v[96:99] offset:12288
	ds_write_b128 v174, v[112:115] offset:45056
	global_load_dwordx4 v[84:87], v172, s[0:1] offset:256
	global_load_dwordx4 v[100:103], v172, s[4:5] offset:256
	global_load_dwordx4 v[88:91], v173, s[0:1] offset:256
	global_load_dwordx4 v[104:107], v173, s[4:5] offset:256
	global_load_dwordx4 v[92:95], v183, s[0:1] offset:256
	global_load_dwordx4 v[108:111], v183, s[4:5] offset:256
	global_load_dwordx4 v[96:99], v2, s[0:1] offset:256
	global_load_dwordx4 v[112:115], v2, s[4:5] offset:256
	s_waitcnt lgkmcnt(0)
	s_barrier
	ds_read_b128 v[68:71], v176
	ds_read_b128 v[116:119], v177 offset:32768
	ds_read_b128 v[72:75], v176 offset:2048
	ds_read_b128 v[120:123], v177 offset:34816
	ds_read_b128 v[76:79], v176 offset:4096
	ds_read_b128 v[124:127], v177 offset:36864
	ds_read_b128 v[80:83], v176 offset:6144
	ds_read_b128 v[128:131], v177 offset:38912
	s_waitcnt lgkmcnt(0)
	v_mfma_f32_16x16x32_bf16 v[64:67], v[68:71], v[116:119], 0
	ds_read_b128 v[152:155], v178
	s_waitcnt vmcnt(8)
	ds_write_b128 v174, v[184:187] offset:16384
	v_mfma_f32_16x16x32_bf16 v[48:51], v[68:71], v[120:123], 0
	ds_read_b128 v[168:171], v179 offset:32768
	ds_write_b128 v174, v[200:203] offset:49152
	v_mfma_f32_16x16x32_bf16 v[32:35], v[68:71], v[124:127], 0
	ds_read_b128 v[156:159], v178 offset:2048
	ds_write_b128 v174, v[188:191] offset:20480
	v_mfma_f32_16x16x32_bf16 v[16:19], v[68:71], v[128:131], 0
	ds_read_b128 v[240:243], v179 offset:34816
	ds_write_b128 v174, v[204:207] offset:53248
	v_mfma_f32_16x16x32_bf16 v[60:63], v[72:75], v[116:119], 0
	ds_read_b128 v[160:163], v178 offset:4096
	ds_write_b128 v174, v[192:195] offset:24576
	v_mfma_f32_16x16x32_bf16 v[44:47], v[72:75], v[120:123], 0
	ds_read_b128 v[244:247], v179 offset:36864
	ds_write_b128 v174, v[208:211] offset:57344
	v_mfma_f32_16x16x32_bf16 v[28:31], v[72:75], v[124:127], 0
	ds_read_b128 v[164:167], v178 offset:6144
	ds_write_b128 v174, v[196:199] offset:28672
	v_mfma_f32_16x16x32_bf16 v[12:15], v[72:75], v[128:131], 0
	ds_read_b128 v[248:251], v179 offset:38912
	ds_write_b128 v174, v[212:215] offset:61440
	v_mfma_f32_16x16x32_bf16 v[56:59], v[76:79], v[116:119], 0
	global_load_dwordx4 v[184:187], v172, s[0:1] offset:384
	v_mfma_f32_16x16x32_bf16 v[40:43], v[76:79], v[120:123], 0
	global_load_dwordx4 v[200:203], v172, s[4:5] offset:384
	v_mfma_f32_16x16x32_bf16 v[24:27], v[76:79], v[124:127], 0
	global_load_dwordx4 v[188:191], v173, s[0:1] offset:384
	v_mfma_f32_16x16x32_bf16 v[4:7], v[76:79], v[128:131], 0
	global_load_dwordx4 v[204:207], v173, s[4:5] offset:384
	v_mfma_f32_16x16x32_bf16 v[52:55], v[80:83], v[116:119], 0
	global_load_dwordx4 v[192:195], v183, s[0:1] offset:384
	v_mfma_f32_16x16x32_bf16 v[36:39], v[80:83], v[120:123], 0
	global_load_dwordx4 v[208:211], v183, s[4:5] offset:384
	v_mfma_f32_16x16x32_bf16 v[20:23], v[80:83], v[124:127], 0
	global_load_dwordx4 v[196:199], v2, s[0:1] offset:384
	v_mfma_f32_16x16x32_bf16 v[8:11], v[80:83], v[128:131], 0
	global_load_dwordx4 v[212:215], v2, s[4:5] offset:384
	s_waitcnt lgkmcnt(0)
	s_barrier
	v_mfma_f32_16x16x32_bf16 v[64:67], v[152:155], v[168:171], v[64:67]
	ds_read_b128 v[68:71], v176 offset:16384
	v_mfma_f32_16x16x32_bf16 v[48:51], v[152:155], v[240:243], v[48:51]
	ds_read_b128 v[116:119], v177 offset:49152
	v_mfma_f32_16x16x32_bf16 v[32:35], v[152:155], v[244:247], v[32:35]
	ds_read_b128 v[72:75], v176 offset:18432
	v_mfma_f32_16x16x32_bf16 v[16:19], v[152:155], v[248:251], v[16:19]
	ds_read_b128 v[120:123], v177 offset:51200
	v_mfma_f32_16x16x32_bf16 v[60:63], v[156:159], v[168:171], v[60:63]
	ds_read_b128 v[76:79], v176 offset:20480
	v_mfma_f32_16x16x32_bf16 v[44:47], v[156:159], v[240:243], v[44:47]
	ds_read_b128 v[124:127], v177 offset:53248
	v_mfma_f32_16x16x32_bf16 v[28:31], v[156:159], v[244:247], v[28:31]
	ds_read_b128 v[80:83], v176 offset:22528
	v_mfma_f32_16x16x32_bf16 v[12:15], v[156:159], v[248:251], v[12:15]
	ds_read_b128 v[128:131], v177 offset:55296
	v_mfma_f32_16x16x32_bf16 v[56:59], v[160:163], v[168:171], v[56:59]
	v_mfma_f32_16x16x32_bf16 v[40:43], v[160:163], v[240:243], v[40:43]
	v_mfma_f32_16x16x32_bf16 v[24:27], v[160:163], v[244:247], v[24:27]
	v_mfma_f32_16x16x32_bf16 v[4:7], v[160:163], v[248:251], v[4:7]
	v_mfma_f32_16x16x32_bf16 v[52:55], v[164:167], v[168:171], v[52:55]
	v_mfma_f32_16x16x32_bf16 v[36:39], v[164:167], v[240:243], v[36:39]
	v_mfma_f32_16x16x32_bf16 v[20:23], v[164:167], v[244:247], v[20:23]
	v_mfma_f32_16x16x32_bf16 v[8:11], v[164:167], v[248:251], v[8:11]
	s_waitcnt lgkmcnt(0)
	v_mfma_f32_16x16x32_bf16 v[64:67], v[68:71], v[116:119], v[64:67]
	ds_read_b128 v[152:155], v178 offset:16384
	s_waitcnt vmcnt(8)
	ds_write_b128 v174, v[84:87]
	v_mfma_f32_16x16x32_bf16 v[48:51], v[68:71], v[120:123], v[48:51]
	ds_read_b128 v[168:171], v179 offset:49152
	ds_write_b128 v174, v[100:103] offset:32768
	v_mfma_f32_16x16x32_bf16 v[32:35], v[68:71], v[124:127], v[32:35]
	ds_read_b128 v[156:159], v178 offset:18432
	ds_write_b128 v174, v[88:91] offset:4096
	v_mfma_f32_16x16x32_bf16 v[16:19], v[68:71], v[128:131], v[16:19]
	ds_read_b128 v[240:243], v179 offset:51200
	ds_write_b128 v174, v[104:107] offset:36864
	v_mfma_f32_16x16x32_bf16 v[60:63], v[72:75], v[116:119], v[60:63]
	ds_read_b128 v[160:163], v178 offset:20480
	ds_write_b128 v174, v[92:95] offset:8192
	v_mfma_f32_16x16x32_bf16 v[44:47], v[72:75], v[120:123], v[44:47]
	ds_read_b128 v[244:247], v179 offset:53248
	ds_write_b128 v174, v[108:111] offset:40960
	v_mfma_f32_16x16x32_bf16 v[28:31], v[72:75], v[124:127], v[28:31]
	ds_read_b128 v[164:167], v178 offset:22528
	ds_write_b128 v174, v[96:99] offset:12288
	v_mfma_f32_16x16x32_bf16 v[12:15], v[72:75], v[128:131], v[12:15]
	ds_read_b128 v[248:251], v179 offset:55296
	ds_write_b128 v174, v[112:115] offset:45056
	v_mfma_f32_16x16x32_bf16 v[56:59], v[76:79], v[116:119], v[56:59]
	global_load_dwordx4 v[84:87], v172, s[0:1] offset:512
	v_mfma_f32_16x16x32_bf16 v[40:43], v[76:79], v[120:123], v[40:43]
	global_load_dwordx4 v[100:103], v172, s[4:5] offset:512
	v_mfma_f32_16x16x32_bf16 v[24:27], v[76:79], v[124:127], v[24:27]
	global_load_dwordx4 v[88:91], v173, s[0:1] offset:512
	v_mfma_f32_16x16x32_bf16 v[4:7], v[76:79], v[128:131], v[4:7]
	global_load_dwordx4 v[104:107], v173, s[4:5] offset:512
	v_mfma_f32_16x16x32_bf16 v[52:55], v[80:83], v[116:119], v[52:55]
	global_load_dwordx4 v[92:95], v183, s[0:1] offset:512
	v_mfma_f32_16x16x32_bf16 v[36:39], v[80:83], v[120:123], v[36:39]
	global_load_dwordx4 v[108:111], v183, s[4:5] offset:512
	v_mfma_f32_16x16x32_bf16 v[20:23], v[80:83], v[124:127], v[20:23]
	global_load_dwordx4 v[96:99], v2, s[0:1] offset:512
	v_mfma_f32_16x16x32_bf16 v[8:11], v[80:83], v[128:131], v[8:11]
	global_load_dwordx4 v[112:115], v2, s[4:5] offset:512
	s_waitcnt lgkmcnt(0)
	s_barrier
	v_mfma_f32_16x16x32_bf16 v[64:67], v[152:155], v[168:171], v[64:67]
	ds_read_b128 v[68:71], v176
	v_mfma_f32_16x16x32_bf16 v[48:51], v[152:155], v[240:243], v[48:51]
	ds_read_b128 v[116:119], v177 offset:32768
	v_mfma_f32_16x16x32_bf16 v[32:35], v[152:155], v[244:247], v[32:35]
	ds_read_b128 v[72:75], v176 offset:2048
	v_mfma_f32_16x16x32_bf16 v[16:19], v[152:155], v[248:251], v[16:19]
	ds_read_b128 v[120:123], v177 offset:34816
	v_mfma_f32_16x16x32_bf16 v[60:63], v[156:159], v[168:171], v[60:63]
	ds_read_b128 v[76:79], v176 offset:4096
	v_mfma_f32_16x16x32_bf16 v[44:47], v[156:159], v[240:243], v[44:47]
	ds_read_b128 v[124:127], v177 offset:36864
	v_mfma_f32_16x16x32_bf16 v[28:31], v[156:159], v[244:247], v[28:31]
	ds_read_b128 v[80:83], v176 offset:6144
	v_mfma_f32_16x16x32_bf16 v[12:15], v[156:159], v[248:251], v[12:15]
	ds_read_b128 v[128:131], v177 offset:38912
	v_mfma_f32_16x16x32_bf16 v[56:59], v[160:163], v[168:171], v[56:59]
	v_mfma_f32_16x16x32_bf16 v[40:43], v[160:163], v[240:243], v[40:43]
	v_mfma_f32_16x16x32_bf16 v[24:27], v[160:163], v[244:247], v[24:27]
	v_mfma_f32_16x16x32_bf16 v[4:7], v[160:163], v[248:251], v[4:7]
	v_mfma_f32_16x16x32_bf16 v[52:55], v[164:167], v[168:171], v[52:55]
	v_mfma_f32_16x16x32_bf16 v[36:39], v[164:167], v[240:243], v[36:39]
	v_mfma_f32_16x16x32_bf16 v[20:23], v[164:167], v[244:247], v[20:23]
	v_mfma_f32_16x16x32_bf16 v[8:11], v[164:167], v[248:251], v[8:11]
	s_waitcnt lgkmcnt(0)
	v_mfma_f32_16x16x32_bf16 v[64:67], v[68:71], v[116:119], v[64:67]
	ds_read_b128 v[152:155], v178
	s_waitcnt vmcnt(8)
	ds_write_b128 v174, v[184:187] offset:16384
	v_mfma_f32_16x16x32_bf16 v[48:51], v[68:71], v[120:123], v[48:51]
	ds_read_b128 v[168:171], v179 offset:32768
	ds_write_b128 v174, v[200:203] offset:49152
	v_mfma_f32_16x16x32_bf16 v[32:35], v[68:71], v[124:127], v[32:35]
	ds_read_b128 v[156:159], v178 offset:2048
	ds_write_b128 v174, v[188:191] offset:20480
	v_mfma_f32_16x16x32_bf16 v[16:19], v[68:71], v[128:131], v[16:19]
	ds_read_b128 v[240:243], v179 offset:34816
	ds_write_b128 v174, v[204:207] offset:53248
	v_mfma_f32_16x16x32_bf16 v[60:63], v[72:75], v[116:119], v[60:63]
	ds_read_b128 v[160:163], v178 offset:4096
	ds_write_b128 v174, v[192:195] offset:24576
	v_mfma_f32_16x16x32_bf16 v[44:47], v[72:75], v[120:123], v[44:47]
	ds_read_b128 v[244:247], v179 offset:36864
	ds_write_b128 v174, v[208:211] offset:57344
	v_mfma_f32_16x16x32_bf16 v[28:31], v[72:75], v[124:127], v[28:31]
	ds_read_b128 v[164:167], v178 offset:6144
	ds_write_b128 v174, v[196:199] offset:28672
	v_mfma_f32_16x16x32_bf16 v[12:15], v[72:75], v[128:131], v[12:15]
	ds_read_b128 v[248:251], v179 offset:38912
	ds_write_b128 v174, v[212:215] offset:61440
	v_mfma_f32_16x16x32_bf16 v[56:59], v[76:79], v[116:119], v[56:59]
	global_load_dwordx4 v[184:187], v172, s[0:1] offset:640
	v_mfma_f32_16x16x32_bf16 v[40:43], v[76:79], v[120:123], v[40:43]
	global_load_dwordx4 v[200:203], v172, s[4:5] offset:640
	v_mfma_f32_16x16x32_bf16 v[24:27], v[76:79], v[124:127], v[24:27]
	global_load_dwordx4 v[188:191], v173, s[0:1] offset:640
	v_mfma_f32_16x16x32_bf16 v[4:7], v[76:79], v[128:131], v[4:7]
	global_load_dwordx4 v[204:207], v173, s[4:5] offset:640
	v_mfma_f32_16x16x32_bf16 v[52:55], v[80:83], v[116:119], v[52:55]
	global_load_dwordx4 v[192:195], v183, s[0:1] offset:640
	v_mfma_f32_16x16x32_bf16 v[36:39], v[80:83], v[120:123], v[36:39]
	global_load_dwordx4 v[208:211], v183, s[4:5] offset:640
	v_mfma_f32_16x16x32_bf16 v[20:23], v[80:83], v[124:127], v[20:23]
	global_load_dwordx4 v[196:199], v2, s[0:1] offset:640
	v_mfma_f32_16x16x32_bf16 v[8:11], v[80:83], v[128:131], v[8:11]
	global_load_dwordx4 v[212:215], v2, s[4:5] offset:640
	s_waitcnt lgkmcnt(0)
	s_barrier
	v_mfma_f32_16x16x32_bf16 v[64:67], v[152:155], v[168:171], v[64:67]
	ds_read_b128 v[68:71], v176 offset:16384
	v_mfma_f32_16x16x32_bf16 v[48:51], v[152:155], v[240:243], v[48:51]
	ds_read_b128 v[116:119], v177 offset:49152
	v_mfma_f32_16x16x32_bf16 v[32:35], v[152:155], v[244:247], v[32:35]
	ds_read_b128 v[72:75], v176 offset:18432
	v_mfma_f32_16x16x32_bf16 v[16:19], v[152:155], v[248:251], v[16:19]
	ds_read_b128 v[120:123], v177 offset:51200
	v_mfma_f32_16x16x32_bf16 v[60:63], v[156:159], v[168:171], v[60:63]
	ds_read_b128 v[76:79], v176 offset:20480
	v_mfma_f32_16x16x32_bf16 v[44:47], v[156:159], v[240:243], v[44:47]
	ds_read_b128 v[124:127], v177 offset:53248
	v_mfma_f32_16x16x32_bf16 v[28:31], v[156:159], v[244:247], v[28:31]
	ds_read_b128 v[80:83], v176 offset:22528
	v_mfma_f32_16x16x32_bf16 v[12:15], v[156:159], v[248:251], v[12:15]
	ds_read_b128 v[128:131], v177 offset:55296
	v_mfma_f32_16x16x32_bf16 v[56:59], v[160:163], v[168:171], v[56:59]
	v_mfma_f32_16x16x32_bf16 v[40:43], v[160:163], v[240:243], v[40:43]
	v_mfma_f32_16x16x32_bf16 v[24:27], v[160:163], v[244:247], v[24:27]
	v_mfma_f32_16x16x32_bf16 v[4:7], v[160:163], v[248:251], v[4:7]
	v_mfma_f32_16x16x32_bf16 v[52:55], v[164:167], v[168:171], v[52:55]
	v_mfma_f32_16x16x32_bf16 v[36:39], v[164:167], v[240:243], v[36:39]
	v_mfma_f32_16x16x32_bf16 v[20:23], v[164:167], v[244:247], v[20:23]
	v_mfma_f32_16x16x32_bf16 v[8:11], v[164:167], v[248:251], v[8:11]
	s_waitcnt lgkmcnt(0)
	v_mfma_f32_16x16x32_bf16 v[64:67], v[68:71], v[116:119], v[64:67]
	ds_read_b128 v[152:155], v178 offset:16384
	s_waitcnt vmcnt(8)
	ds_write_b128 v174, v[84:87]
	v_mfma_f32_16x16x32_bf16 v[48:51], v[68:71], v[120:123], v[48:51]
	ds_read_b128 v[168:171], v179 offset:49152
	ds_write_b128 v174, v[100:103] offset:32768
	v_mfma_f32_16x16x32_bf16 v[32:35], v[68:71], v[124:127], v[32:35]
	ds_read_b128 v[156:159], v178 offset:18432
	ds_write_b128 v174, v[88:91] offset:4096
	v_mfma_f32_16x16x32_bf16 v[16:19], v[68:71], v[128:131], v[16:19]
	ds_read_b128 v[240:243], v179 offset:51200
	ds_write_b128 v174, v[104:107] offset:36864
	v_mfma_f32_16x16x32_bf16 v[60:63], v[72:75], v[116:119], v[60:63]
	ds_read_b128 v[160:163], v178 offset:20480
	ds_write_b128 v174, v[92:95] offset:8192
	v_mfma_f32_16x16x32_bf16 v[44:47], v[72:75], v[120:123], v[44:47]
	ds_read_b128 v[244:247], v179 offset:53248
	ds_write_b128 v174, v[108:111] offset:40960
	v_mfma_f32_16x16x32_bf16 v[28:31], v[72:75], v[124:127], v[28:31]
	ds_read_b128 v[164:167], v178 offset:22528
	ds_write_b128 v174, v[96:99] offset:12288
	v_mfma_f32_16x16x32_bf16 v[12:15], v[72:75], v[128:131], v[12:15]
	ds_read_b128 v[248:251], v179 offset:55296
	ds_write_b128 v174, v[112:115] offset:45056
	v_mfma_f32_16x16x32_bf16 v[56:59], v[76:79], v[116:119], v[56:59]
	global_load_dwordx4 v[84:87], v172, s[0:1] offset:768
	v_mfma_f32_16x16x32_bf16 v[40:43], v[76:79], v[120:123], v[40:43]
	global_load_dwordx4 v[100:103], v172, s[4:5] offset:768
	v_mfma_f32_16x16x32_bf16 v[24:27], v[76:79], v[124:127], v[24:27]
	global_load_dwordx4 v[88:91], v173, s[0:1] offset:768
	v_mfma_f32_16x16x32_bf16 v[4:7], v[76:79], v[128:131], v[4:7]
	global_load_dwordx4 v[104:107], v173, s[4:5] offset:768
	v_mfma_f32_16x16x32_bf16 v[52:55], v[80:83], v[116:119], v[52:55]
	global_load_dwordx4 v[92:95], v183, s[0:1] offset:768
	v_mfma_f32_16x16x32_bf16 v[36:39], v[80:83], v[120:123], v[36:39]
	global_load_dwordx4 v[108:111], v183, s[4:5] offset:768
	v_mfma_f32_16x16x32_bf16 v[20:23], v[80:83], v[124:127], v[20:23]
	global_load_dwordx4 v[96:99], v2, s[0:1] offset:768
	v_mfma_f32_16x16x32_bf16 v[8:11], v[80:83], v[128:131], v[8:11]
	global_load_dwordx4 v[112:115], v2, s[4:5] offset:768
	s_waitcnt lgkmcnt(0)
	s_barrier
	v_mfma_f32_16x16x32_bf16 v[64:67], v[152:155], v[168:171], v[64:67]
	ds_read_b128 v[68:71], v176
	v_mfma_f32_16x16x32_bf16 v[48:51], v[152:155], v[240:243], v[48:51]
	ds_read_b128 v[116:119], v177 offset:32768
	v_mfma_f32_16x16x32_bf16 v[32:35], v[152:155], v[244:247], v[32:35]
	ds_read_b128 v[72:75], v176 offset:2048
	v_mfma_f32_16x16x32_bf16 v[16:19], v[152:155], v[248:251], v[16:19]
	ds_read_b128 v[120:123], v177 offset:34816
	v_mfma_f32_16x16x32_bf16 v[60:63], v[156:159], v[168:171], v[60:63]
	ds_read_b128 v[76:79], v176 offset:4096
	v_mfma_f32_16x16x32_bf16 v[44:47], v[156:159], v[240:243], v[44:47]
	ds_read_b128 v[124:127], v177 offset:36864
	v_mfma_f32_16x16x32_bf16 v[28:31], v[156:159], v[244:247], v[28:31]
	ds_read_b128 v[80:83], v176 offset:6144
	v_mfma_f32_16x16x32_bf16 v[12:15], v[156:159], v[248:251], v[12:15]
	ds_read_b128 v[128:131], v177 offset:38912
	v_mfma_f32_16x16x32_bf16 v[56:59], v[160:163], v[168:171], v[56:59]
	v_mfma_f32_16x16x32_bf16 v[40:43], v[160:163], v[240:243], v[40:43]
	v_mfma_f32_16x16x32_bf16 v[24:27], v[160:163], v[244:247], v[24:27]
	v_mfma_f32_16x16x32_bf16 v[4:7], v[160:163], v[248:251], v[4:7]
	v_mfma_f32_16x16x32_bf16 v[52:55], v[164:167], v[168:171], v[52:55]
	v_mfma_f32_16x16x32_bf16 v[36:39], v[164:167], v[240:243], v[36:39]
	v_mfma_f32_16x16x32_bf16 v[20:23], v[164:167], v[244:247], v[20:23]
	v_mfma_f32_16x16x32_bf16 v[8:11], v[164:167], v[248:251], v[8:11]
	s_waitcnt lgkmcnt(0)
	v_mfma_f32_16x16x32_bf16 v[64:67], v[68:71], v[116:119], v[64:67]
	ds_read_b128 v[152:155], v178
	s_waitcnt vmcnt(8)
	ds_write_b128 v174, v[184:187] offset:16384
	v_mfma_f32_16x16x32_bf16 v[48:51], v[68:71], v[120:123], v[48:51]
	ds_read_b128 v[168:171], v179 offset:32768
	ds_write_b128 v174, v[200:203] offset:49152
	v_mfma_f32_16x16x32_bf16 v[32:35], v[68:71], v[124:127], v[32:35]
	ds_read_b128 v[156:159], v178 offset:2048
	ds_write_b128 v174, v[188:191] offset:20480
	v_mfma_f32_16x16x32_bf16 v[16:19], v[68:71], v[128:131], v[16:19]
	ds_read_b128 v[240:243], v179 offset:34816
	ds_write_b128 v174, v[204:207] offset:53248
	v_mfma_f32_16x16x32_bf16 v[60:63], v[72:75], v[116:119], v[60:63]
	ds_read_b128 v[160:163], v178 offset:4096
	ds_write_b128 v174, v[192:195] offset:24576
	v_mfma_f32_16x16x32_bf16 v[44:47], v[72:75], v[120:123], v[44:47]
	ds_read_b128 v[244:247], v179 offset:36864
	ds_write_b128 v174, v[208:211] offset:57344
	v_mfma_f32_16x16x32_bf16 v[28:31], v[72:75], v[124:127], v[28:31]
	ds_read_b128 v[164:167], v178 offset:6144
	ds_write_b128 v174, v[196:199] offset:28672
	v_mfma_f32_16x16x32_bf16 v[12:15], v[72:75], v[128:131], v[12:15]
	ds_read_b128 v[248:251], v179 offset:38912
	ds_write_b128 v174, v[212:215] offset:61440
	v_mfma_f32_16x16x32_bf16 v[56:59], v[76:79], v[116:119], v[56:59]
	global_load_dwordx4 v[184:187], v172, s[0:1] offset:896
	v_mfma_f32_16x16x32_bf16 v[40:43], v[76:79], v[120:123], v[40:43]
	global_load_dwordx4 v[200:203], v172, s[4:5] offset:896
	v_mfma_f32_16x16x32_bf16 v[24:27], v[76:79], v[124:127], v[24:27]
	global_load_dwordx4 v[188:191], v173, s[0:1] offset:896
	v_mfma_f32_16x16x32_bf16 v[4:7], v[76:79], v[128:131], v[4:7]
	global_load_dwordx4 v[204:207], v173, s[4:5] offset:896
	v_mfma_f32_16x16x32_bf16 v[52:55], v[80:83], v[116:119], v[52:55]
	global_load_dwordx4 v[192:195], v183, s[0:1] offset:896
	v_mfma_f32_16x16x32_bf16 v[36:39], v[80:83], v[120:123], v[36:39]
	global_load_dwordx4 v[208:211], v183, s[4:5] offset:896
	v_mfma_f32_16x16x32_bf16 v[20:23], v[80:83], v[124:127], v[20:23]
	global_load_dwordx4 v[196:199], v2, s[0:1] offset:896
	v_mfma_f32_16x16x32_bf16 v[8:11], v[80:83], v[128:131], v[8:11]
	global_load_dwordx4 v[212:215], v2, s[4:5] offset:896
	s_waitcnt lgkmcnt(0)
	s_barrier
	v_mfma_f32_16x16x32_bf16 v[64:67], v[152:155], v[168:171], v[64:67]
	ds_read_b128 v[68:71], v176 offset:16384
	v_mfma_f32_16x16x32_bf16 v[48:51], v[152:155], v[240:243], v[48:51]
	ds_read_b128 v[116:119], v177 offset:49152
	v_mfma_f32_16x16x32_bf16 v[32:35], v[152:155], v[244:247], v[32:35]
	ds_read_b128 v[72:75], v176 offset:18432
	v_mfma_f32_16x16x32_bf16 v[16:19], v[152:155], v[248:251], v[16:19]
	ds_read_b128 v[120:123], v177 offset:51200
	v_mfma_f32_16x16x32_bf16 v[60:63], v[156:159], v[168:171], v[60:63]
	ds_read_b128 v[76:79], v176 offset:20480
	v_mfma_f32_16x16x32_bf16 v[44:47], v[156:159], v[240:243], v[44:47]
	ds_read_b128 v[124:127], v177 offset:53248
	v_mfma_f32_16x16x32_bf16 v[28:31], v[156:159], v[244:247], v[28:31]
	ds_read_b128 v[80:83], v176 offset:22528
	v_mfma_f32_16x16x32_bf16 v[12:15], v[156:159], v[248:251], v[12:15]
	ds_read_b128 v[128:131], v177 offset:55296
	v_mfma_f32_16x16x32_bf16 v[56:59], v[160:163], v[168:171], v[56:59]
	v_mfma_f32_16x16x32_bf16 v[40:43], v[160:163], v[240:243], v[40:43]
	v_mfma_f32_16x16x32_bf16 v[24:27], v[160:163], v[244:247], v[24:27]
	v_mfma_f32_16x16x32_bf16 v[4:7], v[160:163], v[248:251], v[4:7]
	v_mfma_f32_16x16x32_bf16 v[52:55], v[164:167], v[168:171], v[52:55]
	v_mfma_f32_16x16x32_bf16 v[36:39], v[164:167], v[240:243], v[36:39]
	v_mfma_f32_16x16x32_bf16 v[20:23], v[164:167], v[244:247], v[20:23]
	v_mfma_f32_16x16x32_bf16 v[8:11], v[164:167], v[248:251], v[8:11]
	s_waitcnt lgkmcnt(0)
	v_mfma_f32_16x16x32_bf16 v[64:67], v[68:71], v[116:119], v[64:67]
	ds_read_b128 v[152:155], v178 offset:16384
	s_waitcnt vmcnt(8)
	ds_write_b128 v174, v[84:87]
	v_mfma_f32_16x16x32_bf16 v[48:51], v[68:71], v[120:123], v[48:51]
	ds_read_b128 v[168:171], v179 offset:49152
	ds_write_b128 v174, v[100:103] offset:32768
	v_mfma_f32_16x16x32_bf16 v[32:35], v[68:71], v[124:127], v[32:35]
	ds_read_b128 v[156:159], v178 offset:18432
	ds_write_b128 v174, v[88:91] offset:4096
	v_mfma_f32_16x16x32_bf16 v[16:19], v[68:71], v[128:131], v[16:19]
	ds_read_b128 v[240:243], v179 offset:51200
	ds_write_b128 v174, v[104:107] offset:36864
	v_mfma_f32_16x16x32_bf16 v[60:63], v[72:75], v[116:119], v[60:63]
	ds_read_b128 v[160:163], v178 offset:20480
	ds_write_b128 v174, v[92:95] offset:8192
	v_mfma_f32_16x16x32_bf16 v[44:47], v[72:75], v[120:123], v[44:47]
	ds_read_b128 v[244:247], v179 offset:53248
	ds_write_b128 v174, v[108:111] offset:40960
	v_mfma_f32_16x16x32_bf16 v[28:31], v[72:75], v[124:127], v[28:31]
	ds_read_b128 v[164:167], v178 offset:22528
	ds_write_b128 v174, v[96:99] offset:12288
	v_mfma_f32_16x16x32_bf16 v[12:15], v[72:75], v[128:131], v[12:15]
	ds_read_b128 v[248:251], v179 offset:55296
	ds_write_b128 v174, v[112:115] offset:45056
	v_mfma_f32_16x16x32_bf16 v[56:59], v[76:79], v[116:119], v[56:59]
	global_load_dwordx4 v[84:87], v172, s[0:1] offset:1024
	v_mfma_f32_16x16x32_bf16 v[40:43], v[76:79], v[120:123], v[40:43]
	global_load_dwordx4 v[100:103], v172, s[4:5] offset:1024
	v_mfma_f32_16x16x32_bf16 v[24:27], v[76:79], v[124:127], v[24:27]
	global_load_dwordx4 v[88:91], v173, s[0:1] offset:1024
	v_mfma_f32_16x16x32_bf16 v[4:7], v[76:79], v[128:131], v[4:7]
	global_load_dwordx4 v[104:107], v173, s[4:5] offset:1024
	v_mfma_f32_16x16x32_bf16 v[52:55], v[80:83], v[116:119], v[52:55]
	global_load_dwordx4 v[92:95], v183, s[0:1] offset:1024
	v_mfma_f32_16x16x32_bf16 v[36:39], v[80:83], v[120:123], v[36:39]
	global_load_dwordx4 v[108:111], v183, s[4:5] offset:1024
	v_mfma_f32_16x16x32_bf16 v[20:23], v[80:83], v[124:127], v[20:23]
	global_load_dwordx4 v[96:99], v2, s[0:1] offset:1024
	v_mfma_f32_16x16x32_bf16 v[8:11], v[80:83], v[128:131], v[8:11]
	global_load_dwordx4 v[112:115], v2, s[4:5] offset:1024
	s_waitcnt lgkmcnt(0)
	s_barrier
	v_mfma_f32_16x16x32_bf16 v[64:67], v[152:155], v[168:171], v[64:67]
	ds_read_b128 v[68:71], v176
	v_mfma_f32_16x16x32_bf16 v[48:51], v[152:155], v[240:243], v[48:51]
	ds_read_b128 v[116:119], v177 offset:32768
	v_mfma_f32_16x16x32_bf16 v[32:35], v[152:155], v[244:247], v[32:35]
	ds_read_b128 v[72:75], v176 offset:2048
	v_mfma_f32_16x16x32_bf16 v[16:19], v[152:155], v[248:251], v[16:19]
	ds_read_b128 v[120:123], v177 offset:34816
	v_mfma_f32_16x16x32_bf16 v[60:63], v[156:159], v[168:171], v[60:63]
	ds_read_b128 v[76:79], v176 offset:4096
	v_mfma_f32_16x16x32_bf16 v[44:47], v[156:159], v[240:243], v[44:47]
	ds_read_b128 v[124:127], v177 offset:36864
	v_mfma_f32_16x16x32_bf16 v[28:31], v[156:159], v[244:247], v[28:31]
	ds_read_b128 v[80:83], v176 offset:6144
	v_mfma_f32_16x16x32_bf16 v[12:15], v[156:159], v[248:251], v[12:15]
	ds_read_b128 v[128:131], v177 offset:38912
	v_mfma_f32_16x16x32_bf16 v[56:59], v[160:163], v[168:171], v[56:59]
	v_mfma_f32_16x16x32_bf16 v[40:43], v[160:163], v[240:243], v[40:43]
	v_mfma_f32_16x16x32_bf16 v[24:27], v[160:163], v[244:247], v[24:27]
	v_mfma_f32_16x16x32_bf16 v[4:7], v[160:163], v[248:251], v[4:7]
	v_mfma_f32_16x16x32_bf16 v[52:55], v[164:167], v[168:171], v[52:55]
	v_mfma_f32_16x16x32_bf16 v[36:39], v[164:167], v[240:243], v[36:39]
	v_mfma_f32_16x16x32_bf16 v[20:23], v[164:167], v[244:247], v[20:23]
	v_mfma_f32_16x16x32_bf16 v[8:11], v[164:167], v[248:251], v[8:11]
	s_waitcnt lgkmcnt(0)
	v_mfma_f32_16x16x32_bf16 v[64:67], v[68:71], v[116:119], v[64:67]
	ds_read_b128 v[152:155], v178
	s_waitcnt vmcnt(8)
	ds_write_b128 v174, v[184:187] offset:16384
	v_mfma_f32_16x16x32_bf16 v[48:51], v[68:71], v[120:123], v[48:51]
	ds_read_b128 v[168:171], v179 offset:32768
	ds_write_b128 v174, v[200:203] offset:49152
	v_mfma_f32_16x16x32_bf16 v[32:35], v[68:71], v[124:127], v[32:35]
	ds_read_b128 v[156:159], v178 offset:2048
	ds_write_b128 v174, v[188:191] offset:20480
	v_mfma_f32_16x16x32_bf16 v[16:19], v[68:71], v[128:131], v[16:19]
	ds_read_b128 v[240:243], v179 offset:34816
	ds_write_b128 v174, v[204:207] offset:53248
	v_mfma_f32_16x16x32_bf16 v[60:63], v[72:75], v[116:119], v[60:63]
	ds_read_b128 v[160:163], v178 offset:4096
	ds_write_b128 v174, v[192:195] offset:24576
	v_mfma_f32_16x16x32_bf16 v[44:47], v[72:75], v[120:123], v[44:47]
	ds_read_b128 v[244:247], v179 offset:36864
	ds_write_b128 v174, v[208:211] offset:57344
	v_mfma_f32_16x16x32_bf16 v[28:31], v[72:75], v[124:127], v[28:31]
	ds_read_b128 v[164:167], v178 offset:6144
	ds_write_b128 v174, v[196:199] offset:28672
	v_mfma_f32_16x16x32_bf16 v[12:15], v[72:75], v[128:131], v[12:15]
	ds_read_b128 v[248:251], v179 offset:38912
	ds_write_b128 v174, v[212:215] offset:61440
	v_mfma_f32_16x16x32_bf16 v[56:59], v[76:79], v[116:119], v[56:59]
	global_load_dwordx4 v[184:187], v172, s[0:1] offset:1152
	v_mfma_f32_16x16x32_bf16 v[40:43], v[76:79], v[120:123], v[40:43]
	global_load_dwordx4 v[200:203], v172, s[4:5] offset:1152
	v_mfma_f32_16x16x32_bf16 v[24:27], v[76:79], v[124:127], v[24:27]
	global_load_dwordx4 v[188:191], v173, s[0:1] offset:1152
	v_mfma_f32_16x16x32_bf16 v[4:7], v[76:79], v[128:131], v[4:7]
	global_load_dwordx4 v[204:207], v173, s[4:5] offset:1152
	v_mfma_f32_16x16x32_bf16 v[52:55], v[80:83], v[116:119], v[52:55]
	global_load_dwordx4 v[192:195], v183, s[0:1] offset:1152
	v_mfma_f32_16x16x32_bf16 v[36:39], v[80:83], v[120:123], v[36:39]
	global_load_dwordx4 v[208:211], v183, s[4:5] offset:1152
	v_mfma_f32_16x16x32_bf16 v[20:23], v[80:83], v[124:127], v[20:23]
	global_load_dwordx4 v[196:199], v2, s[0:1] offset:1152
	v_mfma_f32_16x16x32_bf16 v[8:11], v[80:83], v[128:131], v[8:11]
	global_load_dwordx4 v[212:215], v2, s[4:5] offset:1152
	s_waitcnt lgkmcnt(0)
	s_barrier
	v_mfma_f32_16x16x32_bf16 v[64:67], v[152:155], v[168:171], v[64:67]
	ds_read_b128 v[68:71], v176 offset:16384
	v_mfma_f32_16x16x32_bf16 v[48:51], v[152:155], v[240:243], v[48:51]
	ds_read_b128 v[116:119], v177 offset:49152
	v_mfma_f32_16x16x32_bf16 v[32:35], v[152:155], v[244:247], v[32:35]
	ds_read_b128 v[72:75], v176 offset:18432
	v_mfma_f32_16x16x32_bf16 v[16:19], v[152:155], v[248:251], v[16:19]
	ds_read_b128 v[120:123], v177 offset:51200
	v_mfma_f32_16x16x32_bf16 v[60:63], v[156:159], v[168:171], v[60:63]
	ds_read_b128 v[76:79], v176 offset:20480
	v_mfma_f32_16x16x32_bf16 v[44:47], v[156:159], v[240:243], v[44:47]
	ds_read_b128 v[124:127], v177 offset:53248
	v_mfma_f32_16x16x32_bf16 v[28:31], v[156:159], v[244:247], v[28:31]
	ds_read_b128 v[80:83], v176 offset:22528
	v_mfma_f32_16x16x32_bf16 v[12:15], v[156:159], v[248:251], v[12:15]
	ds_read_b128 v[128:131], v177 offset:55296
	v_mfma_f32_16x16x32_bf16 v[56:59], v[160:163], v[168:171], v[56:59]
	v_mfma_f32_16x16x32_bf16 v[40:43], v[160:163], v[240:243], v[40:43]
	v_mfma_f32_16x16x32_bf16 v[24:27], v[160:163], v[244:247], v[24:27]
	v_mfma_f32_16x16x32_bf16 v[4:7], v[160:163], v[248:251], v[4:7]
	v_mfma_f32_16x16x32_bf16 v[52:55], v[164:167], v[168:171], v[52:55]
	v_mfma_f32_16x16x32_bf16 v[36:39], v[164:167], v[240:243], v[36:39]
	v_mfma_f32_16x16x32_bf16 v[20:23], v[164:167], v[244:247], v[20:23]
	v_mfma_f32_16x16x32_bf16 v[8:11], v[164:167], v[248:251], v[8:11]
	s_waitcnt lgkmcnt(0)
	v_mfma_f32_16x16x32_bf16 v[64:67], v[68:71], v[116:119], v[64:67]
	ds_read_b128 v[152:155], v178 offset:16384
	s_waitcnt vmcnt(8)
	ds_write_b128 v174, v[84:87]
	v_mfma_f32_16x16x32_bf16 v[48:51], v[68:71], v[120:123], v[48:51]
	ds_read_b128 v[168:171], v179 offset:49152
	ds_write_b128 v174, v[100:103] offset:32768
	v_mfma_f32_16x16x32_bf16 v[32:35], v[68:71], v[124:127], v[32:35]
	ds_read_b128 v[156:159], v178 offset:18432
	ds_write_b128 v174, v[88:91] offset:4096
	v_mfma_f32_16x16x32_bf16 v[16:19], v[68:71], v[128:131], v[16:19]
	ds_read_b128 v[240:243], v179 offset:51200
	ds_write_b128 v174, v[104:107] offset:36864
	v_mfma_f32_16x16x32_bf16 v[60:63], v[72:75], v[116:119], v[60:63]
	ds_read_b128 v[160:163], v178 offset:20480
	ds_write_b128 v174, v[92:95] offset:8192
	v_mfma_f32_16x16x32_bf16 v[44:47], v[72:75], v[120:123], v[44:47]
	ds_read_b128 v[244:247], v179 offset:53248
	ds_write_b128 v174, v[108:111] offset:40960
	v_mfma_f32_16x16x32_bf16 v[28:31], v[72:75], v[124:127], v[28:31]
	ds_read_b128 v[164:167], v178 offset:22528
	ds_write_b128 v174, v[96:99] offset:12288
	v_mfma_f32_16x16x32_bf16 v[12:15], v[72:75], v[128:131], v[12:15]
	ds_read_b128 v[248:251], v179 offset:55296
	ds_write_b128 v174, v[112:115] offset:45056
	v_mfma_f32_16x16x32_bf16 v[56:59], v[76:79], v[116:119], v[56:59]
	global_load_dwordx4 v[84:87], v172, s[0:1] offset:1280
	v_mfma_f32_16x16x32_bf16 v[40:43], v[76:79], v[120:123], v[40:43]
	global_load_dwordx4 v[100:103], v172, s[4:5] offset:1280
	v_mfma_f32_16x16x32_bf16 v[24:27], v[76:79], v[124:127], v[24:27]
	global_load_dwordx4 v[88:91], v173, s[0:1] offset:1280
	v_mfma_f32_16x16x32_bf16 v[4:7], v[76:79], v[128:131], v[4:7]
	global_load_dwordx4 v[104:107], v173, s[4:5] offset:1280
	v_mfma_f32_16x16x32_bf16 v[52:55], v[80:83], v[116:119], v[52:55]
	global_load_dwordx4 v[92:95], v183, s[0:1] offset:1280
	v_mfma_f32_16x16x32_bf16 v[36:39], v[80:83], v[120:123], v[36:39]
	global_load_dwordx4 v[108:111], v183, s[4:5] offset:1280
	v_mfma_f32_16x16x32_bf16 v[20:23], v[80:83], v[124:127], v[20:23]
	global_load_dwordx4 v[96:99], v2, s[0:1] offset:1280
	v_mfma_f32_16x16x32_bf16 v[8:11], v[80:83], v[128:131], v[8:11]
	global_load_dwordx4 v[112:115], v2, s[4:5] offset:1280
	s_waitcnt lgkmcnt(0)
	s_barrier
	v_mfma_f32_16x16x32_bf16 v[64:67], v[152:155], v[168:171], v[64:67]
	ds_read_b128 v[68:71], v176
	v_mfma_f32_16x16x32_bf16 v[48:51], v[152:155], v[240:243], v[48:51]
	ds_read_b128 v[116:119], v177 offset:32768
	v_mfma_f32_16x16x32_bf16 v[32:35], v[152:155], v[244:247], v[32:35]
	ds_read_b128 v[72:75], v176 offset:2048
	v_mfma_f32_16x16x32_bf16 v[16:19], v[152:155], v[248:251], v[16:19]
	ds_read_b128 v[120:123], v177 offset:34816
	v_mfma_f32_16x16x32_bf16 v[60:63], v[156:159], v[168:171], v[60:63]
	ds_read_b128 v[76:79], v176 offset:4096
	v_mfma_f32_16x16x32_bf16 v[44:47], v[156:159], v[240:243], v[44:47]
	ds_read_b128 v[124:127], v177 offset:36864
	v_mfma_f32_16x16x32_bf16 v[28:31], v[156:159], v[244:247], v[28:31]
	ds_read_b128 v[80:83], v176 offset:6144
	v_mfma_f32_16x16x32_bf16 v[12:15], v[156:159], v[248:251], v[12:15]
	ds_read_b128 v[128:131], v177 offset:38912
	v_mfma_f32_16x16x32_bf16 v[56:59], v[160:163], v[168:171], v[56:59]
	v_mfma_f32_16x16x32_bf16 v[40:43], v[160:163], v[240:243], v[40:43]
	v_mfma_f32_16x16x32_bf16 v[24:27], v[160:163], v[244:247], v[24:27]
	v_mfma_f32_16x16x32_bf16 v[4:7], v[160:163], v[248:251], v[4:7]
	v_mfma_f32_16x16x32_bf16 v[52:55], v[164:167], v[168:171], v[52:55]
	v_mfma_f32_16x16x32_bf16 v[36:39], v[164:167], v[240:243], v[36:39]
	v_mfma_f32_16x16x32_bf16 v[20:23], v[164:167], v[244:247], v[20:23]
	v_mfma_f32_16x16x32_bf16 v[8:11], v[164:167], v[248:251], v[8:11]
	s_waitcnt lgkmcnt(0)
	v_mfma_f32_16x16x32_bf16 v[64:67], v[68:71], v[116:119], v[64:67]
	ds_read_b128 v[152:155], v178
	s_waitcnt vmcnt(8)
	ds_write_b128 v174, v[184:187] offset:16384
	v_mfma_f32_16x16x32_bf16 v[48:51], v[68:71], v[120:123], v[48:51]
	ds_read_b128 v[168:171], v179 offset:32768
	ds_write_b128 v174, v[200:203] offset:49152
	v_mfma_f32_16x16x32_bf16 v[32:35], v[68:71], v[124:127], v[32:35]
	ds_read_b128 v[156:159], v178 offset:2048
	ds_write_b128 v174, v[188:191] offset:20480
	v_mfma_f32_16x16x32_bf16 v[16:19], v[68:71], v[128:131], v[16:19]
	ds_read_b128 v[240:243], v179 offset:34816
	ds_write_b128 v174, v[204:207] offset:53248
	v_mfma_f32_16x16x32_bf16 v[60:63], v[72:75], v[116:119], v[60:63]
	ds_read_b128 v[160:163], v178 offset:4096
	ds_write_b128 v174, v[192:195] offset:24576
	v_mfma_f32_16x16x32_bf16 v[44:47], v[72:75], v[120:123], v[44:47]
	ds_read_b128 v[244:247], v179 offset:36864
	ds_write_b128 v174, v[208:211] offset:57344
	v_mfma_f32_16x16x32_bf16 v[28:31], v[72:75], v[124:127], v[28:31]
	ds_read_b128 v[164:167], v178 offset:6144
	ds_write_b128 v174, v[196:199] offset:28672
	v_mfma_f32_16x16x32_bf16 v[12:15], v[72:75], v[128:131], v[12:15]
	ds_read_b128 v[248:251], v179 offset:38912
	ds_write_b128 v174, v[212:215] offset:61440
	v_mfma_f32_16x16x32_bf16 v[56:59], v[76:79], v[116:119], v[56:59]
	global_load_dwordx4 v[184:187], v172, s[0:1] offset:1408
	v_mfma_f32_16x16x32_bf16 v[40:43], v[76:79], v[120:123], v[40:43]
	global_load_dwordx4 v[200:203], v172, s[4:5] offset:1408
	v_mfma_f32_16x16x32_bf16 v[24:27], v[76:79], v[124:127], v[24:27]
	global_load_dwordx4 v[188:191], v173, s[0:1] offset:1408
	v_mfma_f32_16x16x32_bf16 v[4:7], v[76:79], v[128:131], v[4:7]
	global_load_dwordx4 v[204:207], v173, s[4:5] offset:1408
	v_mfma_f32_16x16x32_bf16 v[52:55], v[80:83], v[116:119], v[52:55]
	global_load_dwordx4 v[192:195], v183, s[0:1] offset:1408
	v_mfma_f32_16x16x32_bf16 v[36:39], v[80:83], v[120:123], v[36:39]
	global_load_dwordx4 v[208:211], v183, s[4:5] offset:1408
	v_mfma_f32_16x16x32_bf16 v[20:23], v[80:83], v[124:127], v[20:23]
	global_load_dwordx4 v[196:199], v2, s[0:1] offset:1408
	v_mfma_f32_16x16x32_bf16 v[8:11], v[80:83], v[128:131], v[8:11]
	global_load_dwordx4 v[212:215], v2, s[4:5] offset:1408
	s_waitcnt lgkmcnt(0)
	s_barrier
	v_mfma_f32_16x16x32_bf16 v[64:67], v[152:155], v[168:171], v[64:67]
	ds_read_b128 v[68:71], v176 offset:16384
	v_mfma_f32_16x16x32_bf16 v[48:51], v[152:155], v[240:243], v[48:51]
	ds_read_b128 v[116:119], v177 offset:49152
	v_mfma_f32_16x16x32_bf16 v[32:35], v[152:155], v[244:247], v[32:35]
	ds_read_b128 v[72:75], v176 offset:18432
	v_mfma_f32_16x16x32_bf16 v[16:19], v[152:155], v[248:251], v[16:19]
	ds_read_b128 v[120:123], v177 offset:51200
	v_mfma_f32_16x16x32_bf16 v[60:63], v[156:159], v[168:171], v[60:63]
	ds_read_b128 v[76:79], v176 offset:20480
	v_mfma_f32_16x16x32_bf16 v[44:47], v[156:159], v[240:243], v[44:47]
	ds_read_b128 v[124:127], v177 offset:53248
	v_mfma_f32_16x16x32_bf16 v[28:31], v[156:159], v[244:247], v[28:31]
	ds_read_b128 v[80:83], v176 offset:22528
	v_mfma_f32_16x16x32_bf16 v[12:15], v[156:159], v[248:251], v[12:15]
	ds_read_b128 v[128:131], v177 offset:55296
	v_mfma_f32_16x16x32_bf16 v[56:59], v[160:163], v[168:171], v[56:59]
	v_mfma_f32_16x16x32_bf16 v[40:43], v[160:163], v[240:243], v[40:43]
	v_mfma_f32_16x16x32_bf16 v[24:27], v[160:163], v[244:247], v[24:27]
	v_mfma_f32_16x16x32_bf16 v[4:7], v[160:163], v[248:251], v[4:7]
	v_mfma_f32_16x16x32_bf16 v[52:55], v[164:167], v[168:171], v[52:55]
	v_mfma_f32_16x16x32_bf16 v[36:39], v[164:167], v[240:243], v[36:39]
	v_mfma_f32_16x16x32_bf16 v[20:23], v[164:167], v[244:247], v[20:23]
	v_mfma_f32_16x16x32_bf16 v[8:11], v[164:167], v[248:251], v[8:11]
	s_waitcnt lgkmcnt(0)
	v_mfma_f32_16x16x32_bf16 v[64:67], v[68:71], v[116:119], v[64:67]
	ds_read_b128 v[152:155], v178 offset:16384
	s_waitcnt vmcnt(8)
	ds_write_b128 v174, v[84:87]
	v_mfma_f32_16x16x32_bf16 v[48:51], v[68:71], v[120:123], v[48:51]
	ds_read_b128 v[168:171], v179 offset:49152
	ds_write_b128 v174, v[100:103] offset:32768
	v_mfma_f32_16x16x32_bf16 v[32:35], v[68:71], v[124:127], v[32:35]
	ds_read_b128 v[156:159], v178 offset:18432
	ds_write_b128 v174, v[88:91] offset:4096
	v_mfma_f32_16x16x32_bf16 v[16:19], v[68:71], v[128:131], v[16:19]
	ds_read_b128 v[240:243], v179 offset:51200
	ds_write_b128 v174, v[104:107] offset:36864
	v_mfma_f32_16x16x32_bf16 v[60:63], v[72:75], v[116:119], v[60:63]
	ds_read_b128 v[160:163], v178 offset:20480
	ds_write_b128 v174, v[92:95] offset:8192
	v_mfma_f32_16x16x32_bf16 v[44:47], v[72:75], v[120:123], v[44:47]
	ds_read_b128 v[244:247], v179 offset:53248
	ds_write_b128 v174, v[108:111] offset:40960
	v_mfma_f32_16x16x32_bf16 v[28:31], v[72:75], v[124:127], v[28:31]
	ds_read_b128 v[164:167], v178 offset:22528
	ds_write_b128 v174, v[96:99] offset:12288
	v_mfma_f32_16x16x32_bf16 v[12:15], v[72:75], v[128:131], v[12:15]
	ds_read_b128 v[248:251], v179 offset:55296
	ds_write_b128 v174, v[112:115] offset:45056
	v_mfma_f32_16x16x32_bf16 v[56:59], v[76:79], v[116:119], v[56:59]
	global_load_dwordx4 v[84:87], v172, s[0:1] offset:1536
	v_mfma_f32_16x16x32_bf16 v[40:43], v[76:79], v[120:123], v[40:43]
	global_load_dwordx4 v[100:103], v172, s[4:5] offset:1536
	v_mfma_f32_16x16x32_bf16 v[24:27], v[76:79], v[124:127], v[24:27]
	global_load_dwordx4 v[88:91], v173, s[0:1] offset:1536
	v_mfma_f32_16x16x32_bf16 v[4:7], v[76:79], v[128:131], v[4:7]
	global_load_dwordx4 v[104:107], v173, s[4:5] offset:1536
	v_mfma_f32_16x16x32_bf16 v[52:55], v[80:83], v[116:119], v[52:55]
	global_load_dwordx4 v[92:95], v183, s[0:1] offset:1536
	v_mfma_f32_16x16x32_bf16 v[36:39], v[80:83], v[120:123], v[36:39]
	global_load_dwordx4 v[108:111], v183, s[4:5] offset:1536
	v_mfma_f32_16x16x32_bf16 v[20:23], v[80:83], v[124:127], v[20:23]
	global_load_dwordx4 v[96:99], v2, s[0:1] offset:1536
	v_mfma_f32_16x16x32_bf16 v[8:11], v[80:83], v[128:131], v[8:11]
	global_load_dwordx4 v[112:115], v2, s[4:5] offset:1536
	s_waitcnt lgkmcnt(0)
	s_barrier
	v_mfma_f32_16x16x32_bf16 v[64:67], v[152:155], v[168:171], v[64:67]
	ds_read_b128 v[68:71], v176
	v_mfma_f32_16x16x32_bf16 v[48:51], v[152:155], v[240:243], v[48:51]
	ds_read_b128 v[116:119], v177 offset:32768
	v_mfma_f32_16x16x32_bf16 v[32:35], v[152:155], v[244:247], v[32:35]
	ds_read_b128 v[72:75], v176 offset:2048
	v_mfma_f32_16x16x32_bf16 v[16:19], v[152:155], v[248:251], v[16:19]
	ds_read_b128 v[120:123], v177 offset:34816
	v_mfma_f32_16x16x32_bf16 v[60:63], v[156:159], v[168:171], v[60:63]
	ds_read_b128 v[76:79], v176 offset:4096
	v_mfma_f32_16x16x32_bf16 v[44:47], v[156:159], v[240:243], v[44:47]
	ds_read_b128 v[124:127], v177 offset:36864
	v_mfma_f32_16x16x32_bf16 v[28:31], v[156:159], v[244:247], v[28:31]
	ds_read_b128 v[80:83], v176 offset:6144
	v_mfma_f32_16x16x32_bf16 v[12:15], v[156:159], v[248:251], v[12:15]
	ds_read_b128 v[128:131], v177 offset:38912
	v_mfma_f32_16x16x32_bf16 v[56:59], v[160:163], v[168:171], v[56:59]
	v_mfma_f32_16x16x32_bf16 v[40:43], v[160:163], v[240:243], v[40:43]
	v_mfma_f32_16x16x32_bf16 v[24:27], v[160:163], v[244:247], v[24:27]
	v_mfma_f32_16x16x32_bf16 v[4:7], v[160:163], v[248:251], v[4:7]
	v_mfma_f32_16x16x32_bf16 v[52:55], v[164:167], v[168:171], v[52:55]
	v_mfma_f32_16x16x32_bf16 v[36:39], v[164:167], v[240:243], v[36:39]
	v_mfma_f32_16x16x32_bf16 v[20:23], v[164:167], v[244:247], v[20:23]
	v_mfma_f32_16x16x32_bf16 v[8:11], v[164:167], v[248:251], v[8:11]
	s_waitcnt lgkmcnt(0)
	v_mfma_f32_16x16x32_bf16 v[64:67], v[68:71], v[116:119], v[64:67]
	ds_read_b128 v[152:155], v178
	s_waitcnt vmcnt(8)
	ds_write_b128 v174, v[184:187] offset:16384
	v_mfma_f32_16x16x32_bf16 v[48:51], v[68:71], v[120:123], v[48:51]
	ds_read_b128 v[168:171], v179 offset:32768
	ds_write_b128 v174, v[200:203] offset:49152
	v_mfma_f32_16x16x32_bf16 v[32:35], v[68:71], v[124:127], v[32:35]
	ds_read_b128 v[156:159], v178 offset:2048
	ds_write_b128 v174, v[188:191] offset:20480
	v_mfma_f32_16x16x32_bf16 v[16:19], v[68:71], v[128:131], v[16:19]
	ds_read_b128 v[240:243], v179 offset:34816
	ds_write_b128 v174, v[204:207] offset:53248
	v_mfma_f32_16x16x32_bf16 v[60:63], v[72:75], v[116:119], v[60:63]
	ds_read_b128 v[160:163], v178 offset:4096
	ds_write_b128 v174, v[192:195] offset:24576
	v_mfma_f32_16x16x32_bf16 v[44:47], v[72:75], v[120:123], v[44:47]
	ds_read_b128 v[244:247], v179 offset:36864
	ds_write_b128 v174, v[208:211] offset:57344
	v_mfma_f32_16x16x32_bf16 v[28:31], v[72:75], v[124:127], v[28:31]
	ds_read_b128 v[164:167], v178 offset:6144
	ds_write_b128 v174, v[196:199] offset:28672
	v_mfma_f32_16x16x32_bf16 v[12:15], v[72:75], v[128:131], v[12:15]
	ds_read_b128 v[248:251], v179 offset:38912
	ds_write_b128 v174, v[212:215] offset:61440
	v_mfma_f32_16x16x32_bf16 v[56:59], v[76:79], v[116:119], v[56:59]
	global_load_dwordx4 v[184:187], v172, s[0:1] offset:1664
	v_mfma_f32_16x16x32_bf16 v[40:43], v[76:79], v[120:123], v[40:43]
	global_load_dwordx4 v[200:203], v172, s[4:5] offset:1664
	v_mfma_f32_16x16x32_bf16 v[24:27], v[76:79], v[124:127], v[24:27]
	global_load_dwordx4 v[188:191], v173, s[0:1] offset:1664
	v_mfma_f32_16x16x32_bf16 v[4:7], v[76:79], v[128:131], v[4:7]
	global_load_dwordx4 v[204:207], v173, s[4:5] offset:1664
	v_mfma_f32_16x16x32_bf16 v[52:55], v[80:83], v[116:119], v[52:55]
	global_load_dwordx4 v[192:195], v183, s[0:1] offset:1664
	v_mfma_f32_16x16x32_bf16 v[36:39], v[80:83], v[120:123], v[36:39]
	global_load_dwordx4 v[208:211], v183, s[4:5] offset:1664
	v_mfma_f32_16x16x32_bf16 v[20:23], v[80:83], v[124:127], v[20:23]
	global_load_dwordx4 v[196:199], v2, s[0:1] offset:1664
	v_mfma_f32_16x16x32_bf16 v[8:11], v[80:83], v[128:131], v[8:11]
	global_load_dwordx4 v[212:215], v2, s[4:5] offset:1664
	s_waitcnt lgkmcnt(0)
	s_barrier
	v_mfma_f32_16x16x32_bf16 v[64:67], v[152:155], v[168:171], v[64:67]
	ds_read_b128 v[68:71], v176 offset:16384
	v_mfma_f32_16x16x32_bf16 v[48:51], v[152:155], v[240:243], v[48:51]
	ds_read_b128 v[116:119], v177 offset:49152
	v_mfma_f32_16x16x32_bf16 v[32:35], v[152:155], v[244:247], v[32:35]
	ds_read_b128 v[72:75], v176 offset:18432
	v_mfma_f32_16x16x32_bf16 v[16:19], v[152:155], v[248:251], v[16:19]
	ds_read_b128 v[120:123], v177 offset:51200
	v_mfma_f32_16x16x32_bf16 v[60:63], v[156:159], v[168:171], v[60:63]
	ds_read_b128 v[76:79], v176 offset:20480
	v_mfma_f32_16x16x32_bf16 v[44:47], v[156:159], v[240:243], v[44:47]
	ds_read_b128 v[124:127], v177 offset:53248
	v_mfma_f32_16x16x32_bf16 v[28:31], v[156:159], v[244:247], v[28:31]
	ds_read_b128 v[80:83], v176 offset:22528
	v_mfma_f32_16x16x32_bf16 v[12:15], v[156:159], v[248:251], v[12:15]
	ds_read_b128 v[128:131], v177 offset:55296
	v_mfma_f32_16x16x32_bf16 v[56:59], v[160:163], v[168:171], v[56:59]
	v_mfma_f32_16x16x32_bf16 v[40:43], v[160:163], v[240:243], v[40:43]
	v_mfma_f32_16x16x32_bf16 v[24:27], v[160:163], v[244:247], v[24:27]
	v_mfma_f32_16x16x32_bf16 v[4:7], v[160:163], v[248:251], v[4:7]
	v_mfma_f32_16x16x32_bf16 v[52:55], v[164:167], v[168:171], v[52:55]
	v_mfma_f32_16x16x32_bf16 v[36:39], v[164:167], v[240:243], v[36:39]
	v_mfma_f32_16x16x32_bf16 v[20:23], v[164:167], v[244:247], v[20:23]
	v_mfma_f32_16x16x32_bf16 v[8:11], v[164:167], v[248:251], v[8:11]
	s_waitcnt lgkmcnt(0)
	v_mfma_f32_16x16x32_bf16 v[64:67], v[68:71], v[116:119], v[64:67]
	ds_read_b128 v[152:155], v178 offset:16384
	s_waitcnt vmcnt(8)
	ds_write_b128 v174, v[84:87]
	v_mfma_f32_16x16x32_bf16 v[48:51], v[68:71], v[120:123], v[48:51]
	ds_read_b128 v[168:171], v179 offset:49152
	ds_write_b128 v174, v[100:103] offset:32768
	v_mfma_f32_16x16x32_bf16 v[32:35], v[68:71], v[124:127], v[32:35]
	ds_read_b128 v[156:159], v178 offset:18432
	ds_write_b128 v174, v[88:91] offset:4096
	v_mfma_f32_16x16x32_bf16 v[16:19], v[68:71], v[128:131], v[16:19]
	ds_read_b128 v[240:243], v179 offset:51200
	ds_write_b128 v174, v[104:107] offset:36864
	v_mfma_f32_16x16x32_bf16 v[60:63], v[72:75], v[116:119], v[60:63]
	ds_read_b128 v[160:163], v178 offset:20480
	ds_write_b128 v174, v[92:95] offset:8192
	v_mfma_f32_16x16x32_bf16 v[44:47], v[72:75], v[120:123], v[44:47]
	ds_read_b128 v[244:247], v179 offset:53248
	ds_write_b128 v174, v[108:111] offset:40960
	v_mfma_f32_16x16x32_bf16 v[28:31], v[72:75], v[124:127], v[28:31]
	ds_read_b128 v[164:167], v178 offset:22528
	ds_write_b128 v174, v[96:99] offset:12288
	v_mfma_f32_16x16x32_bf16 v[12:15], v[72:75], v[128:131], v[12:15]
	ds_read_b128 v[248:251], v179 offset:55296
	ds_write_b128 v174, v[112:115] offset:45056
	v_mfma_f32_16x16x32_bf16 v[56:59], v[76:79], v[116:119], v[56:59]
	global_load_dwordx4 v[84:87], v172, s[0:1] offset:1792
	v_mfma_f32_16x16x32_bf16 v[40:43], v[76:79], v[120:123], v[40:43]
	global_load_dwordx4 v[100:103], v172, s[4:5] offset:1792
	v_mfma_f32_16x16x32_bf16 v[24:27], v[76:79], v[124:127], v[24:27]
	global_load_dwordx4 v[88:91], v173, s[0:1] offset:1792
	v_mfma_f32_16x16x32_bf16 v[4:7], v[76:79], v[128:131], v[4:7]
	global_load_dwordx4 v[104:107], v173, s[4:5] offset:1792
	v_mfma_f32_16x16x32_bf16 v[52:55], v[80:83], v[116:119], v[52:55]
	global_load_dwordx4 v[92:95], v183, s[0:1] offset:1792
	v_mfma_f32_16x16x32_bf16 v[36:39], v[80:83], v[120:123], v[36:39]
	global_load_dwordx4 v[108:111], v183, s[4:5] offset:1792
	v_mfma_f32_16x16x32_bf16 v[20:23], v[80:83], v[124:127], v[20:23]
	global_load_dwordx4 v[96:99], v2, s[0:1] offset:1792
	v_mfma_f32_16x16x32_bf16 v[8:11], v[80:83], v[128:131], v[8:11]
	global_load_dwordx4 v[112:115], v2, s[4:5] offset:1792
	s_waitcnt lgkmcnt(0)
	s_barrier
	v_mfma_f32_16x16x32_bf16 v[64:67], v[152:155], v[168:171], v[64:67]
	ds_read_b128 v[68:71], v176
	v_mfma_f32_16x16x32_bf16 v[48:51], v[152:155], v[240:243], v[48:51]
	ds_read_b128 v[116:119], v177 offset:32768
	v_mfma_f32_16x16x32_bf16 v[32:35], v[152:155], v[244:247], v[32:35]
	ds_read_b128 v[72:75], v176 offset:2048
	v_mfma_f32_16x16x32_bf16 v[16:19], v[152:155], v[248:251], v[16:19]
	ds_read_b128 v[120:123], v177 offset:34816
	v_mfma_f32_16x16x32_bf16 v[60:63], v[156:159], v[168:171], v[60:63]
	ds_read_b128 v[76:79], v176 offset:4096
	v_mfma_f32_16x16x32_bf16 v[44:47], v[156:159], v[240:243], v[44:47]
	ds_read_b128 v[124:127], v177 offset:36864
	v_mfma_f32_16x16x32_bf16 v[28:31], v[156:159], v[244:247], v[28:31]
	ds_read_b128 v[80:83], v176 offset:6144
	v_mfma_f32_16x16x32_bf16 v[12:15], v[156:159], v[248:251], v[12:15]
	ds_read_b128 v[128:131], v177 offset:38912
	v_mfma_f32_16x16x32_bf16 v[56:59], v[160:163], v[168:171], v[56:59]
	v_mfma_f32_16x16x32_bf16 v[40:43], v[160:163], v[240:243], v[40:43]
	v_mfma_f32_16x16x32_bf16 v[24:27], v[160:163], v[244:247], v[24:27]
	v_mfma_f32_16x16x32_bf16 v[4:7], v[160:163], v[248:251], v[4:7]
	v_mfma_f32_16x16x32_bf16 v[52:55], v[164:167], v[168:171], v[52:55]
	v_mfma_f32_16x16x32_bf16 v[36:39], v[164:167], v[240:243], v[36:39]
	v_mfma_f32_16x16x32_bf16 v[20:23], v[164:167], v[244:247], v[20:23]
	v_mfma_f32_16x16x32_bf16 v[8:11], v[164:167], v[248:251], v[8:11]
	s_waitcnt lgkmcnt(0)
	v_mfma_f32_16x16x32_bf16 v[64:67], v[68:71], v[116:119], v[64:67]
	ds_read_b128 v[152:155], v178
	s_waitcnt vmcnt(8)
	ds_write_b128 v174, v[184:187] offset:16384
	v_mfma_f32_16x16x32_bf16 v[48:51], v[68:71], v[120:123], v[48:51]
	ds_read_b128 v[168:171], v179 offset:32768
	ds_write_b128 v174, v[200:203] offset:49152
	v_mfma_f32_16x16x32_bf16 v[32:35], v[68:71], v[124:127], v[32:35]
	ds_read_b128 v[156:159], v178 offset:2048
	ds_write_b128 v174, v[188:191] offset:20480
	v_mfma_f32_16x16x32_bf16 v[16:19], v[68:71], v[128:131], v[16:19]
	ds_read_b128 v[240:243], v179 offset:34816
	ds_write_b128 v174, v[204:207] offset:53248
	v_mfma_f32_16x16x32_bf16 v[60:63], v[72:75], v[116:119], v[60:63]
	ds_read_b128 v[160:163], v178 offset:4096
	ds_write_b128 v174, v[192:195] offset:24576
	v_mfma_f32_16x16x32_bf16 v[44:47], v[72:75], v[120:123], v[44:47]
	ds_read_b128 v[244:247], v179 offset:36864
	ds_write_b128 v174, v[208:211] offset:57344
	v_mfma_f32_16x16x32_bf16 v[28:31], v[72:75], v[124:127], v[28:31]
	ds_read_b128 v[164:167], v178 offset:6144
	ds_write_b128 v174, v[196:199] offset:28672
	v_mfma_f32_16x16x32_bf16 v[12:15], v[72:75], v[128:131], v[12:15]
	ds_read_b128 v[248:251], v179 offset:38912
	ds_write_b128 v174, v[212:215] offset:61440
	v_mfma_f32_16x16x32_bf16 v[56:59], v[76:79], v[116:119], v[56:59]
	global_load_dwordx4 v[184:187], v172, s[0:1] offset:1920
	v_mfma_f32_16x16x32_bf16 v[40:43], v[76:79], v[120:123], v[40:43]
	global_load_dwordx4 v[200:203], v172, s[4:5] offset:1920
	v_mfma_f32_16x16x32_bf16 v[24:27], v[76:79], v[124:127], v[24:27]
	global_load_dwordx4 v[188:191], v173, s[0:1] offset:1920
	v_mfma_f32_16x16x32_bf16 v[4:7], v[76:79], v[128:131], v[4:7]
	global_load_dwordx4 v[204:207], v173, s[4:5] offset:1920
	v_mfma_f32_16x16x32_bf16 v[52:55], v[80:83], v[116:119], v[52:55]
	global_load_dwordx4 v[192:195], v183, s[0:1] offset:1920
	v_mfma_f32_16x16x32_bf16 v[36:39], v[80:83], v[120:123], v[36:39]
	global_load_dwordx4 v[208:211], v183, s[4:5] offset:1920
	v_mfma_f32_16x16x32_bf16 v[20:23], v[80:83], v[124:127], v[20:23]
	global_load_dwordx4 v[196:199], v2, s[0:1] offset:1920
	v_mfma_f32_16x16x32_bf16 v[8:11], v[80:83], v[128:131], v[8:11]
	global_load_dwordx4 v[212:215], v2, s[4:5] offset:1920
	s_waitcnt lgkmcnt(0)
	s_barrier
	v_mfma_f32_16x16x32_bf16 v[64:67], v[152:155], v[168:171], v[64:67]
	ds_read_b128 v[68:71], v176 offset:16384
	v_mfma_f32_16x16x32_bf16 v[48:51], v[152:155], v[240:243], v[48:51]
	ds_read_b128 v[116:119], v177 offset:49152
	v_mfma_f32_16x16x32_bf16 v[32:35], v[152:155], v[244:247], v[32:35]
	ds_read_b128 v[72:75], v176 offset:18432
	v_mfma_f32_16x16x32_bf16 v[16:19], v[152:155], v[248:251], v[16:19]
	ds_read_b128 v[120:123], v177 offset:51200
	v_mfma_f32_16x16x32_bf16 v[60:63], v[156:159], v[168:171], v[60:63]
	ds_read_b128 v[76:79], v176 offset:20480
	v_mfma_f32_16x16x32_bf16 v[44:47], v[156:159], v[240:243], v[44:47]
	ds_read_b128 v[124:127], v177 offset:53248
	v_mfma_f32_16x16x32_bf16 v[28:31], v[156:159], v[244:247], v[28:31]
	ds_read_b128 v[80:83], v176 offset:22528
	v_mfma_f32_16x16x32_bf16 v[12:15], v[156:159], v[248:251], v[12:15]
	ds_read_b128 v[128:131], v177 offset:55296
	v_mfma_f32_16x16x32_bf16 v[56:59], v[160:163], v[168:171], v[56:59]
	v_mfma_f32_16x16x32_bf16 v[40:43], v[160:163], v[240:243], v[40:43]
	v_mfma_f32_16x16x32_bf16 v[24:27], v[160:163], v[244:247], v[24:27]
	v_mfma_f32_16x16x32_bf16 v[4:7], v[160:163], v[248:251], v[4:7]
	v_mfma_f32_16x16x32_bf16 v[52:55], v[164:167], v[168:171], v[52:55]
	v_mfma_f32_16x16x32_bf16 v[36:39], v[164:167], v[240:243], v[36:39]
	v_mfma_f32_16x16x32_bf16 v[20:23], v[164:167], v[244:247], v[20:23]
	v_mfma_f32_16x16x32_bf16 v[8:11], v[164:167], v[248:251], v[8:11]
	s_waitcnt lgkmcnt(0)
	v_readlane_b32 s11, v252, 0
	s_add_i32 s11, s36, s11
	s_cmpk_lt_u32 s11, 0x3b8
	s_cselect_b32 s11, s11, s36
	s_bfe_u32 s0, s11, 0xf0001
	s_mul_i32 s0, s0, 0x89af
	s_lshr_b32 s0, s0, 22
	s_mul_i32 s1, s0, 0xee
	s_sub_i32 s1, s11, s1
	s_mul_i32 s4, s1, 37
	s_lshr_b32 s5, s4, 8
	s_sub_i32 s5, s1, s5
	s_bfe_u32 s5, s5, 0x70001
	s_bfe_u32 s4, s4, 0x80008
	s_add_i32 s5, s5, s4
	s_bfe_u32 s4, s5, 0x60002
	s_mul_i32 s5, s4, 7
	s_sub_i32 s1, s1, s5
	s_and_b32 s6, s1, 0xff
	s_mul_i32 s0, s0, 7
	s_add_i32 s6, s6, s0
	v_readlane_b32 s0, v252, 8
	s_add_i32 s7, s0, s4
	s_lshl_b32 s0, s6, 18
	s_add_u32 s0, s66, s0
	s_addc_u32 s1, s67, 0
	s_lshl_b32 s4, s7, 18
	s_add_u32 s4, s20, s4
	s_addc_u32 s5, s21, 0
	v_mfma_f32_16x16x32_bf16 v[64:67], v[68:71], v[116:119], v[64:67]
	ds_read_b128 v[152:155], v178 offset:16384
	s_waitcnt vmcnt(8)
	ds_write_b128 v174, v[84:87]
	v_mfma_f32_16x16x32_bf16 v[48:51], v[68:71], v[120:123], v[48:51]
	ds_read_b128 v[168:171], v179 offset:49152
	ds_write_b128 v174, v[100:103] offset:32768
	v_mfma_f32_16x16x32_bf16 v[32:35], v[68:71], v[124:127], v[32:35]
	ds_read_b128 v[156:159], v178 offset:18432
	ds_write_b128 v174, v[88:91] offset:4096
	v_mfma_f32_16x16x32_bf16 v[16:19], v[68:71], v[128:131], v[16:19]
	ds_read_b128 v[240:243], v179 offset:51200
	ds_write_b128 v174, v[104:107] offset:36864
	v_mfma_f32_16x16x32_bf16 v[60:63], v[72:75], v[116:119], v[60:63]
	ds_read_b128 v[160:163], v178 offset:20480
	ds_write_b128 v174, v[92:95] offset:8192
	v_mfma_f32_16x16x32_bf16 v[44:47], v[72:75], v[120:123], v[44:47]
	ds_read_b128 v[244:247], v179 offset:53248
	ds_write_b128 v174, v[108:111] offset:40960
	v_mfma_f32_16x16x32_bf16 v[28:31], v[72:75], v[124:127], v[28:31]
	ds_read_b128 v[164:167], v178 offset:22528
	ds_write_b128 v174, v[96:99] offset:12288
	v_mfma_f32_16x16x32_bf16 v[12:15], v[72:75], v[128:131], v[12:15]
	ds_read_b128 v[248:251], v179 offset:55296
	ds_write_b128 v174, v[112:115] offset:45056
	v_mfma_f32_16x16x32_bf16 v[56:59], v[76:79], v[116:119], v[56:59]
	global_load_dwordx4 v[84:87], v172, s[0:1]
	v_mfma_f32_16x16x32_bf16 v[40:43], v[76:79], v[120:123], v[40:43]
	global_load_dwordx4 v[100:103], v172, s[4:5]
	v_mfma_f32_16x16x32_bf16 v[24:27], v[76:79], v[124:127], v[24:27]
	global_load_dwordx4 v[88:91], v173, s[0:1]
	v_mfma_f32_16x16x32_bf16 v[4:7], v[76:79], v[128:131], v[4:7]
	global_load_dwordx4 v[104:107], v173, s[4:5]
	v_mfma_f32_16x16x32_bf16 v[52:55], v[80:83], v[116:119], v[52:55]
	global_load_dwordx4 v[92:95], v183, s[0:1]
	v_mfma_f32_16x16x32_bf16 v[36:39], v[80:83], v[120:123], v[36:39]
	global_load_dwordx4 v[108:111], v183, s[4:5]
	v_mfma_f32_16x16x32_bf16 v[20:23], v[80:83], v[124:127], v[20:23]
	global_load_dwordx4 v[96:99], v2, s[0:1]
	v_mfma_f32_16x16x32_bf16 v[8:11], v[80:83], v[128:131], v[8:11]
	global_load_dwordx4 v[112:115], v2, s[4:5]
	s_waitcnt lgkmcnt(0)
	s_barrier
	v_mfma_f32_16x16x32_bf16 v[64:67], v[152:155], v[168:171], v[64:67]
	ds_read_b128 v[68:71], v176
	v_mfma_f32_16x16x32_bf16 v[48:51], v[152:155], v[240:243], v[48:51]
	ds_read_b128 v[116:119], v177 offset:32768
	v_mfma_f32_16x16x32_bf16 v[32:35], v[152:155], v[244:247], v[32:35]
	ds_read_b128 v[72:75], v176 offset:2048
	v_mfma_f32_16x16x32_bf16 v[16:19], v[152:155], v[248:251], v[16:19]
	ds_read_b128 v[120:123], v177 offset:34816
	v_mfma_f32_16x16x32_bf16 v[60:63], v[156:159], v[168:171], v[60:63]
	ds_read_b128 v[76:79], v176 offset:4096
	v_mfma_f32_16x16x32_bf16 v[44:47], v[156:159], v[240:243], v[44:47]
	ds_read_b128 v[124:127], v177 offset:36864
	v_mfma_f32_16x16x32_bf16 v[28:31], v[156:159], v[244:247], v[28:31]
	ds_read_b128 v[80:83], v176 offset:6144
	v_mfma_f32_16x16x32_bf16 v[12:15], v[156:159], v[248:251], v[12:15]
	ds_read_b128 v[128:131], v177 offset:38912
	v_mfma_f32_16x16x32_bf16 v[56:59], v[160:163], v[168:171], v[56:59]
	v_mfma_f32_16x16x32_bf16 v[40:43], v[160:163], v[240:243], v[40:43]
	v_mfma_f32_16x16x32_bf16 v[24:27], v[160:163], v[244:247], v[24:27]
	v_mfma_f32_16x16x32_bf16 v[4:7], v[160:163], v[248:251], v[4:7]
	v_mfma_f32_16x16x32_bf16 v[52:55], v[164:167], v[168:171], v[52:55]
	v_mfma_f32_16x16x32_bf16 v[36:39], v[164:167], v[240:243], v[36:39]
	v_mfma_f32_16x16x32_bf16 v[20:23], v[164:167], v[244:247], v[20:23]
	v_mfma_f32_16x16x32_bf16 v[8:11], v[164:167], v[248:251], v[8:11]
	s_waitcnt lgkmcnt(0)
	v_mfma_f32_16x16x32_bf16 v[64:67], v[68:71], v[116:119], v[64:67]
	ds_read_b128 v[152:155], v178
	s_waitcnt vmcnt(8)
	ds_write_b128 v174, v[184:187] offset:16384
	v_mfma_f32_16x16x32_bf16 v[48:51], v[68:71], v[120:123], v[48:51]
	ds_read_b128 v[168:171], v179 offset:32768
	ds_write_b128 v174, v[200:203] offset:49152
	v_mfma_f32_16x16x32_bf16 v[32:35], v[68:71], v[124:127], v[32:35]
	ds_read_b128 v[156:159], v178 offset:2048
	ds_write_b128 v174, v[188:191] offset:20480
	v_mfma_f32_16x16x32_bf16 v[16:19], v[68:71], v[128:131], v[16:19]
	ds_read_b128 v[240:243], v179 offset:34816
	ds_write_b128 v174, v[204:207] offset:53248
	v_mfma_f32_16x16x32_bf16 v[60:63], v[72:75], v[116:119], v[60:63]
	ds_read_b128 v[160:163], v178 offset:4096
	ds_write_b128 v174, v[192:195] offset:24576
	v_mfma_f32_16x16x32_bf16 v[44:47], v[72:75], v[120:123], v[44:47]
	ds_read_b128 v[244:247], v179 offset:36864
	ds_write_b128 v174, v[208:211] offset:57344
	v_mfma_f32_16x16x32_bf16 v[28:31], v[72:75], v[124:127], v[28:31]
	ds_read_b128 v[164:167], v178 offset:6144
	ds_write_b128 v174, v[196:199] offset:28672
	v_mfma_f32_16x16x32_bf16 v[12:15], v[72:75], v[128:131], v[12:15]
	ds_read_b128 v[248:251], v179 offset:38912
	ds_write_b128 v174, v[212:215] offset:61440
	v_mfma_f32_16x16x32_bf16 v[56:59], v[76:79], v[116:119], v[56:59]
	global_load_dwordx4 v[184:187], v172, s[0:1] offset:128
	v_mfma_f32_16x16x32_bf16 v[40:43], v[76:79], v[120:123], v[40:43]
	global_load_dwordx4 v[200:203], v172, s[4:5] offset:128
	v_mfma_f32_16x16x32_bf16 v[24:27], v[76:79], v[124:127], v[24:27]
	global_load_dwordx4 v[188:191], v173, s[0:1] offset:128
	v_mfma_f32_16x16x32_bf16 v[4:7], v[76:79], v[128:131], v[4:7]
	global_load_dwordx4 v[204:207], v173, s[4:5] offset:128
	v_mfma_f32_16x16x32_bf16 v[52:55], v[80:83], v[116:119], v[52:55]
	global_load_dwordx4 v[192:195], v183, s[0:1] offset:128
	v_mfma_f32_16x16x32_bf16 v[36:39], v[80:83], v[120:123], v[36:39]
	global_load_dwordx4 v[208:211], v183, s[4:5] offset:128
	v_mfma_f32_16x16x32_bf16 v[20:23], v[80:83], v[124:127], v[20:23]
	global_load_dwordx4 v[196:199], v2, s[0:1] offset:128
	v_mfma_f32_16x16x32_bf16 v[8:11], v[80:83], v[128:131], v[8:11]
	global_load_dwordx4 v[212:215], v2, s[4:5] offset:128
	s_waitcnt lgkmcnt(0)
	s_barrier
	v_mfma_f32_16x16x32_bf16 v[64:67], v[152:155], v[168:171], v[64:67]
	ds_read_b128 v[68:71], v176 offset:16384
	v_mfma_f32_16x16x32_bf16 v[48:51], v[152:155], v[240:243], v[48:51]
	ds_read_b128 v[116:119], v177 offset:49152
	v_mfma_f32_16x16x32_bf16 v[32:35], v[152:155], v[244:247], v[32:35]
	ds_read_b128 v[72:75], v176 offset:18432
	v_mfma_f32_16x16x32_bf16 v[16:19], v[152:155], v[248:251], v[16:19]
	ds_read_b128 v[120:123], v177 offset:51200
	v_mfma_f32_16x16x32_bf16 v[60:63], v[156:159], v[168:171], v[60:63]
	ds_read_b128 v[76:79], v176 offset:20480
	v_mfma_f32_16x16x32_bf16 v[44:47], v[156:159], v[240:243], v[44:47]
	ds_read_b128 v[124:127], v177 offset:53248
	v_mfma_f32_16x16x32_bf16 v[28:31], v[156:159], v[244:247], v[28:31]
	ds_read_b128 v[80:83], v176 offset:22528
	v_mfma_f32_16x16x32_bf16 v[12:15], v[156:159], v[248:251], v[12:15]
	ds_read_b128 v[128:131], v177 offset:55296
	v_mfma_f32_16x16x32_bf16 v[56:59], v[160:163], v[168:171], v[56:59]
	v_mfma_f32_16x16x32_bf16 v[40:43], v[160:163], v[240:243], v[40:43]
	v_mfma_f32_16x16x32_bf16 v[24:27], v[160:163], v[244:247], v[24:27]
	v_mfma_f32_16x16x32_bf16 v[4:7], v[160:163], v[248:251], v[4:7]
	v_mfma_f32_16x16x32_bf16 v[52:55], v[164:167], v[168:171], v[52:55]
	v_mfma_f32_16x16x32_bf16 v[36:39], v[164:167], v[240:243], v[36:39]
	v_mfma_f32_16x16x32_bf16 v[20:23], v[164:167], v[244:247], v[20:23]
	v_mfma_f32_16x16x32_bf16 v[8:11], v[164:167], v[248:251], v[8:11]
	s_waitcnt lgkmcnt(0)
	v_mfma_f32_16x16x32_bf16 v[64:67], v[68:71], v[116:119], v[64:67]
	ds_read_b128 v[152:155], v178 offset:16384
	v_mfma_f32_16x16x32_bf16 v[48:51], v[68:71], v[120:123], v[48:51]
	ds_read_b128 v[168:171], v179 offset:49152
	v_mfma_f32_16x16x32_bf16 v[32:35], v[68:71], v[124:127], v[32:35]
	ds_read_b128 v[156:159], v178 offset:18432
	v_mfma_f32_16x16x32_bf16 v[16:19], v[68:71], v[128:131], v[16:19]
	ds_read_b128 v[240:243], v179 offset:51200
	v_mfma_f32_16x16x32_bf16 v[60:63], v[72:75], v[116:119], v[60:63]
	ds_read_b128 v[160:163], v178 offset:20480
	v_mfma_f32_16x16x32_bf16 v[44:47], v[72:75], v[120:123], v[44:47]
	ds_read_b128 v[244:247], v179 offset:53248
	v_mfma_f32_16x16x32_bf16 v[28:31], v[72:75], v[124:127], v[28:31]
	ds_read_b128 v[164:167], v178 offset:22528
	v_mfma_f32_16x16x32_bf16 v[12:15], v[72:75], v[128:131], v[12:15]
	ds_read_b128 v[248:251], v179 offset:55296
	v_mfma_f32_16x16x32_bf16 v[56:59], v[76:79], v[116:119], v[56:59]
	v_mfma_f32_16x16x32_bf16 v[40:43], v[76:79], v[120:123], v[40:43]
	v_mfma_f32_16x16x32_bf16 v[24:27], v[76:79], v[124:127], v[24:27]
	v_mfma_f32_16x16x32_bf16 v[4:7], v[76:79], v[128:131], v[4:7]
	v_mfma_f32_16x16x32_bf16 v[52:55], v[80:83], v[116:119], v[52:55]
	v_mfma_f32_16x16x32_bf16 v[36:39], v[80:83], v[120:123], v[36:39]
	v_mfma_f32_16x16x32_bf16 v[20:23], v[80:83], v[124:127], v[20:23]
	v_mfma_f32_16x16x32_bf16 v[8:11], v[80:83], v[128:131], v[8:11]
	s_waitcnt lgkmcnt(0)
	s_barrier
	v_mfma_f32_16x16x32_bf16 v[64:67], v[152:155], v[168:171], v[64:67]
	v_mfma_f32_16x16x32_bf16 v[48:51], v[152:155], v[240:243], v[48:51]
	v_mfma_f32_16x16x32_bf16 v[32:35], v[152:155], v[244:247], v[32:35]
	v_mfma_f32_16x16x32_bf16 v[16:19], v[152:155], v[248:251], v[16:19]
	v_mfma_f32_16x16x32_bf16 v[60:63], v[156:159], v[168:171], v[60:63]
	v_mfma_f32_16x16x32_bf16 v[44:47], v[156:159], v[240:243], v[44:47]
	v_mfma_f32_16x16x32_bf16 v[28:31], v[156:159], v[244:247], v[28:31]
	v_mfma_f32_16x16x32_bf16 v[12:15], v[156:159], v[248:251], v[12:15]
	v_mfma_f32_16x16x32_bf16 v[56:59], v[160:163], v[168:171], v[56:59]
	v_mfma_f32_16x16x32_bf16 v[40:43], v[160:163], v[240:243], v[40:43]
	v_mfma_f32_16x16x32_bf16 v[24:27], v[160:163], v[244:247], v[24:27]
	v_mfma_f32_16x16x32_bf16 v[4:7], v[160:163], v[248:251], v[4:7]
	v_mfma_f32_16x16x32_bf16 v[52:55], v[164:167], v[168:171], v[52:55]
	v_mfma_f32_16x16x32_bf16 v[36:39], v[164:167], v[240:243], v[36:39]
	v_mfma_f32_16x16x32_bf16 v[20:23], v[164:167], v[244:247], v[20:23]
	v_mfma_f32_16x16x32_bf16 v[8:11], v[164:167], v[248:251], v[8:11]
	s_nop 7
	s_nop 7

.LBB0_766:
	s_add_i32 s22, s39, 2
	s_cmp_lt_u32 s22, s38
	s_cselect_b64 s[10:11], -1, 0
	s_cmp_ge_u32 s22, s38
	s_cselect_b64 s[12:13], -1, 0
	v_lshl_add_u64 v[254:255], v[150:151], 0, s[0:1]
	ds_read_b128 v[186:189], v240
	ds_read_b128 v[190:193], v240 offset:4608
	ds_read_b128 v[194:197], v240 offset:32
	ds_read_b128 v[198:201], v240 offset:4640
	ds_read_b128 v[202:205], v240 offset:64
	ds_read_b128 v[206:209], v240 offset:4672
	ds_read_b128 v[210:213], v240 offset:96
	ds_read_b128 v[214:217], v240 offset:4704
	s_and_b64 vcc, exec, s[12:13]
	s_cbranch_vccnz .Lat_noload_a
	s_mov_b32 s4, 0x7275000
	s_mov_b32 s5, 0
	s_mov_b32 s6, 0x72ad000
	s_mov_b32 s7, 0
	v_lshl_add_u64 v[248:249], v[254:255], 0, s[4:5]
	v_lshl_add_u64 v[250:251], v[254:255], 0, s[6:7]
	global_load_dwordx4 v[100:103], v[248:249], off offset:1536
	global_load_dwordx4 v[112:115], v[248:249], off offset:2048
	global_load_dwordx4 v[104:107], v[250:251], off offset:1536
	global_load_dwordx4 v[128:131], v[250:251], off offset:2048
.Lat_noload_a:
	s_waitcnt vmcnt(8) lgkmcnt(0)
	v_mfma_f32_32x32x16_bf16 v[68:83], v[186:189], v[120:123], v[224:239]
	ds_read_b64_tr_b16 v[186:187], v241 offset:18432
	ds_read_b64_tr_b16 v[188:189], v241 offset:19584
	v_mfma_f32_32x32x16_bf16 v[84:99], v[190:193], v[120:123], v[224:239]
	ds_read_b64_tr_b16 v[190:191], v241 offset:18496
	ds_read_b64_tr_b16 v[192:193], v241 offset:19648
	v_mfma_f32_32x32x16_bf16 v[68:83], v[194:197], v[108:111], v[68:83]
	ds_read_b64_tr_b16 v[194:195], v241 offset:20736
	ds_read_b64_tr_b16 v[196:197], v241 offset:21888
	v_mfma_f32_32x32x16_bf16 v[84:99], v[198:201], v[108:111], v[84:99]
	ds_read_b64_tr_b16 v[198:199], v241 offset:20800
	ds_read_b64_tr_b16 v[200:201], v241 offset:21952
	v_mfma_f32_32x32x16_bf16 v[154:169], v[202:205], v[116:119], v[224:239]
	ds_read_b64_tr_b16 v[202:203], v242 offset:23040
	ds_read_b64_tr_b16 v[204:205], v242 offset:24192
	v_mfma_f32_32x32x16_bf16 v[170:185], v[206:209], v[116:119], v[224:239]
	ds_read_b64_tr_b16 v[206:207], v242 offset:23104
	ds_read_b64_tr_b16 v[208:209], v242 offset:24256
	v_mfma_f32_32x32x16_bf16 v[154:169], v[210:213], v[124:127], v[154:169]
	ds_read_b64_tr_b16 v[210:211], v242 offset:25344
	ds_read_b64_tr_b16 v[212:213], v242 offset:26496
	v_mfma_f32_32x32x16_bf16 v[170:185], v[214:217], v[124:127], v[170:185]
	ds_read_b64_tr_b16 v[214:215], v242 offset:25408
	ds_read_b64_tr_b16 v[216:217], v242 offset:26560
	v_exp_f32_e32 v68, v68
	v_exp_f32_e32 v69, v69
	v_exp_f32_e32 v70, v70
	v_exp_f32_e32 v71, v71
	v_exp_f32_e32 v72, v72
	v_exp_f32_e32 v73, v73
	v_exp_f32_e32 v74, v74
	v_exp_f32_e32 v75, v75
	v_pk_add_f32 v[220:221], v[68:69], v[220:221]
	v_pk_add_f32 v[220:221], v[70:71], v[220:221]
	v_pk_add_f32 v[220:221], v[72:73], v[220:221]
	v_pk_add_f32 v[220:221], v[74:75], v[220:221]
	v_cvt_pk_bf16_f32 v68, v68, v69
	v_cvt_pk_bf16_f32 v69, v70, v71
	v_cvt_pk_bf16_f32 v70, v72, v73
	v_cvt_pk_bf16_f32 v71, v74, v75
	s_waitcnt lgkmcnt(12)
	s_nop 0
	v_mfma_f32_32x32x16_bf16 v[4:19], v[186:189], v[68:71], v[4:19]
	v_mfma_f32_32x32x16_bf16 v[20:35], v[190:193], v[68:71], v[20:35]
	v_exp_f32_e32 v154, v154
	v_exp_f32_e32 v155, v155
	v_exp_f32_e32 v156, v156
	v_exp_f32_e32 v157, v157
	v_exp_f32_e32 v158, v158
	v_exp_f32_e32 v159, v159
	v_exp_f32_e32 v160, v160
	v_exp_f32_e32 v161, v161
	v_pk_add_f32 v[246:247], v[154:155], v[246:247]
	v_pk_add_f32 v[246:247], v[156:157], v[246:247]
	v_pk_add_f32 v[246:247], v[158:159], v[246:247]
	v_pk_add_f32 v[246:247], v[160:161], v[246:247]
	v_cvt_pk_bf16_f32 v154, v154, v155
	v_cvt_pk_bf16_f32 v155, v156, v157
	v_cvt_pk_bf16_f32 v156, v158, v159
	v_cvt_pk_bf16_f32 v157, v160, v161
	s_nop 1
	v_mfma_f32_32x32x16_bf16 v[36:51], v[186:189], v[154:157], v[36:51]
	v_mfma_f32_32x32x16_bf16 v[52:67], v[190:193], v[154:157], v[52:67]
	v_exp_f32_e32 v76, v76
	v_exp_f32_e32 v77, v77
	v_exp_f32_e32 v78, v78
	v_exp_f32_e32 v79, v79
	v_exp_f32_e32 v80, v80
	v_exp_f32_e32 v81, v81
	v_exp_f32_e32 v82, v82
	v_exp_f32_e32 v83, v83
	v_pk_add_f32 v[220:221], v[76:77], v[220:221]
	v_pk_add_f32 v[220:221], v[78:79], v[220:221]
	v_pk_add_f32 v[220:221], v[80:81], v[220:221]
	v_pk_add_f32 v[220:221], v[82:83], v[220:221]
	v_cvt_pk_bf16_f32 v76, v76, v77
	v_cvt_pk_bf16_f32 v77, v78, v79
	v_cvt_pk_bf16_f32 v78, v80, v81
	v_cvt_pk_bf16_f32 v79, v82, v83
	s_waitcnt lgkmcnt(8)
	s_nop 0
	v_mfma_f32_32x32x16_bf16 v[4:19], v[194:197], v[76:79], v[4:19]
	v_mfma_f32_32x32x16_bf16 v[20:35], v[198:201], v[76:79], v[20:35]
	v_exp_f32_e32 v162, v162
	v_exp_f32_e32 v163, v163
	v_exp_f32_e32 v164, v164
	v_exp_f32_e32 v165, v165
	v_exp_f32_e32 v166, v166
	v_exp_f32_e32 v167, v167
	v_exp_f32_e32 v168, v168
	v_exp_f32_e32 v169, v169
	v_pk_add_f32 v[246:247], v[162:163], v[246:247]
	v_pk_add_f32 v[246:247], v[164:165], v[246:247]
	v_pk_add_f32 v[246:247], v[166:167], v[246:247]
	v_pk_add_f32 v[246:247], v[168:169], v[246:247]
	v_cvt_pk_bf16_f32 v162, v162, v163
	v_cvt_pk_bf16_f32 v163, v164, v165
	v_cvt_pk_bf16_f32 v164, v166, v167
	v_cvt_pk_bf16_f32 v165, v168, v169
	s_nop 1
	v_mfma_f32_32x32x16_bf16 v[36:51], v[194:197], v[162:165], v[36:51]
	v_mfma_f32_32x32x16_bf16 v[52:67], v[198:201], v[162:165], v[52:67]
	v_exp_f32_e32 v84, v84
	v_exp_f32_e32 v85, v85
	v_exp_f32_e32 v86, v86
	v_exp_f32_e32 v87, v87
	v_exp_f32_e32 v88, v88
	v_exp_f32_e32 v89, v89
	v_exp_f32_e32 v90, v90
	v_exp_f32_e32 v91, v91
	v_pk_add_f32 v[220:221], v[84:85], v[220:221]
	v_pk_add_f32 v[220:221], v[86:87], v[220:221]
	v_pk_add_f32 v[220:221], v[88:89], v[220:221]
	v_pk_add_f32 v[220:221], v[90:91], v[220:221]
	v_cvt_pk_bf16_f32 v84, v84, v85
	v_cvt_pk_bf16_f32 v85, v86, v87
	v_cvt_pk_bf16_f32 v86, v88, v89
	v_cvt_pk_bf16_f32 v87, v90, v91
	s_waitcnt lgkmcnt(4)
	s_nop 0
	v_mfma_f32_32x32x16_bf16 v[4:19], v[202:205], v[84:87], v[4:19]
	v_mfma_f32_32x32x16_bf16 v[20:35], v[206:209], v[84:87], v[20:35]
	v_exp_f32_e32 v170, v170
	v_exp_f32_e32 v171, v171
	v_exp_f32_e32 v172, v172
	v_exp_f32_e32 v173, v173
	v_exp_f32_e32 v174, v174
	v_exp_f32_e32 v175, v175
	v_exp_f32_e32 v176, v176
	v_exp_f32_e32 v177, v177
	v_pk_add_f32 v[246:247], v[170:171], v[246:247]
	v_pk_add_f32 v[246:247], v[172:173], v[246:247]
	v_pk_add_f32 v[246:247], v[174:175], v[246:247]
	v_pk_add_f32 v[246:247], v[176:177], v[246:247]
	v_cvt_pk_bf16_f32 v170, v170, v171
	v_cvt_pk_bf16_f32 v171, v172, v173
	v_cvt_pk_bf16_f32 v172, v174, v175
	v_cvt_pk_bf16_f32 v173, v176, v177
	s_nop 1
	v_mfma_f32_32x32x16_bf16 v[36:51], v[202:205], v[170:173], v[36:51]
	v_mfma_f32_32x32x16_bf16 v[52:67], v[206:209], v[170:173], v[52:67]
	v_exp_f32_e32 v92, v92
	v_exp_f32_e32 v93, v93
	v_exp_f32_e32 v94, v94
	v_exp_f32_e32 v95, v95
	v_exp_f32_e32 v96, v96
	v_exp_f32_e32 v97, v97
	v_exp_f32_e32 v98, v98
	v_exp_f32_e32 v99, v99
	v_pk_add_f32 v[220:221], v[92:93], v[220:221]
	v_pk_add_f32 v[220:221], v[94:95], v[220:221]
	v_pk_add_f32 v[220:221], v[96:97], v[220:221]
	v_pk_add_f32 v[220:221], v[98:99], v[220:221]
	v_cvt_pk_bf16_f32 v92, v92, v93
	v_cvt_pk_bf16_f32 v93, v94, v95
	v_cvt_pk_bf16_f32 v94, v96, v97
	v_cvt_pk_bf16_f32 v95, v98, v99
	s_waitcnt lgkmcnt(0)
	s_nop 0
	v_mfma_f32_32x32x16_bf16 v[4:19], v[210:213], v[92:95], v[4:19]
	v_mfma_f32_32x32x16_bf16 v[20:35], v[214:217], v[92:95], v[20:35]
	v_exp_f32_e32 v178, v178
	v_exp_f32_e32 v179, v179
	v_exp_f32_e32 v180, v180
	v_exp_f32_e32 v181, v181
	v_exp_f32_e32 v182, v182
	v_exp_f32_e32 v183, v183
	v_exp_f32_e32 v184, v184
	v_exp_f32_e32 v185, v185
	v_pk_add_f32 v[246:247], v[178:179], v[246:247]
	v_pk_add_f32 v[246:247], v[180:181], v[246:247]
	v_pk_add_f32 v[246:247], v[182:183], v[246:247]
	v_pk_add_f32 v[246:247], v[184:185], v[246:247]
	v_cvt_pk_bf16_f32 v178, v178, v179
	v_cvt_pk_bf16_f32 v179, v180, v181
	v_cvt_pk_bf16_f32 v180, v182, v183
	v_cvt_pk_bf16_f32 v181, v184, v185
	s_nop 1
	v_mfma_f32_32x32x16_bf16 v[36:51], v[210:213], v[178:181], v[36:51]
	v_mfma_f32_32x32x16_bf16 v[52:67], v[214:217], v[178:181], v[52:67]
	v_max3_f32 v248, v220, v221, v246
	v_max_f32_e32 v248, v248, v247
	v_cmp_lt_f32_e32 vcc, 0x49800000, v248
	s_cbranch_vccz .Lat_norescale_a
	v_add_f32_e32 v250, v220, v221
	v_add_f32_e32 v251, v246, v247
	v_lshlrev_b32_e32 v249, 2, v222
	v_xor_b32_e32 v249, 0x80, v249
	v_and_b32_e32 v249, 0xfc, v249
	ds_bpermute_b32 v68, v249, v250
	ds_bpermute_b32 v69, v249, v251
	s_waitcnt lgkmcnt(0)
	v_add_f32_e32 v250, v250, v68
	v_add_f32_e32 v251, v251, v69
	v_max_f32_e32 v250, v250, v251
	v_log_f32_e32 v250, v250
	s_nop 0
	v_max_f32_e32 v250, 0, v250
	v_add_f32_e32 v244, v244, v250
	v_exp_f32_e64 v248, -v250
	v_xor_b32_e32 v224, 0x80000000, v244
	v_mov_b32_e32 v225, v224
	v_mov_b32_e32 v226, v224
	v_mov_b32_e32 v227, v224
	v_mov_b32_e32 v228, v224
	v_mov_b32_e32 v229, v224
	v_mov_b32_e32 v230, v224
	v_mov_b32_e32 v231, v224
	v_mov_b32_e32 v232, v224
	v_mov_b32_e32 v233, v224
	v_mov_b32_e32 v234, v224
	v_mov_b32_e32 v235, v224
	v_mov_b32_e32 v236, v224
	v_mov_b32_e32 v237, v224
	v_mov_b32_e32 v238, v224
	v_mov_b32_e32 v239, v224
	v_mul_f32_e32 v220, v220, v248
	v_mul_f32_e32 v221, v221, v248
	v_mul_f32_e32 v246, v246, v248
	v_mul_f32_e32 v247, v247, v248
	v_pk_mul_f32 v[4:5], v[4:5], v[248:249] op_sel_hi:[1,0]
	v_pk_mul_f32 v[6:7], v[6:7], v[248:249] op_sel_hi:[1,0]
	v_pk_mul_f32 v[8:9], v[8:9], v[248:249] op_sel_hi:[1,0]
	v_pk_mul_f32 v[10:11], v[10:11], v[248:249] op_sel_hi:[1,0]
	v_pk_mul_f32 v[12:13], v[12:13], v[248:249] op_sel_hi:[1,0]
	v_pk_mul_f32 v[14:15], v[14:15], v[248:249] op_sel_hi:[1,0]
	v_pk_mul_f32 v[16:17], v[16:17], v[248:249] op_sel_hi:[1,0]
	v_pk_mul_f32 v[18:19], v[18:19], v[248:249] op_sel_hi:[1,0]
	v_pk_mul_f32 v[20:21], v[20:21], v[248:249] op_sel_hi:[1,0]
	v_pk_mul_f32 v[22:23], v[22:23], v[248:249] op_sel_hi:[1,0]
	v_pk_mul_f32 v[24:25], v[24:25], v[248:249] op_sel_hi:[1,0]
	v_pk_mul_f32 v[26:27], v[26:27], v[248:249] op_sel_hi:[1,0]
	v_pk_mul_f32 v[28:29], v[28:29], v[248:249] op_sel_hi:[1,0]
	v_pk_mul_f32 v[30:31], v[30:31], v[248:249] op_sel_hi:[1,0]
	v_pk_mul_f32 v[32:33], v[32:33], v[248:249] op_sel_hi:[1,0]
	v_pk_mul_f32 v[34:35], v[34:35], v[248:249] op_sel_hi:[1,0]
	v_pk_mul_f32 v[36:37], v[36:37], v[248:249] op_sel_hi:[1,0]
	v_pk_mul_f32 v[38:39], v[38:39], v[248:249] op_sel_hi:[1,0]
	v_pk_mul_f32 v[40:41], v[40:41], v[248:249] op_sel_hi:[1,0]
	v_pk_mul_f32 v[42:43], v[42:43], v[248:249] op_sel_hi:[1,0]
	v_pk_mul_f32 v[44:45], v[44:45], v[248:249] op_sel_hi:[1,0]
	v_pk_mul_f32 v[46:47], v[46:47], v[248:249] op_sel_hi:[1,0]
	v_pk_mul_f32 v[48:49], v[48:49], v[248:249] op_sel_hi:[1,0]
	v_pk_mul_f32 v[50:51], v[50:51], v[248:249] op_sel_hi:[1,0]
	v_pk_mul_f32 v[52:53], v[52:53], v[248:249] op_sel_hi:[1,0]
	v_pk_mul_f32 v[54:55], v[54:55], v[248:249] op_sel_hi:[1,0]
	v_pk_mul_f32 v[56:57], v[56:57], v[248:249] op_sel_hi:[1,0]
	v_pk_mul_f32 v[58:59], v[58:59], v[248:249] op_sel_hi:[1,0]
	v_pk_mul_f32 v[60:61], v[60:61], v[248:249] op_sel_hi:[1,0]
	v_pk_mul_f32 v[62:63], v[62:63], v[248:249] op_sel_hi:[1,0]
	v_pk_mul_f32 v[64:65], v[64:65], v[248:249] op_sel_hi:[1,0]
	v_pk_mul_f32 v[66:67], v[66:67], v[248:249] op_sel_hi:[1,0]
.Lat_norescale_a:
	s_and_b64 vcc, exec, s[10:11]
	s_cbranch_vccnz .Lat_mid_w4
	s_waitcnt vmcnt(0)
	s_branch .Lat_mid_w
.Lat_mid_w4:
	s_waitcnt vmcnt(4)
.Lat_mid_w:
	ds_write_b128 v245, v[132:135] offset:9216
	ds_write_b128 v245, v[136:139] offset:13824
	ds_write_b128 v245, v[140:143] offset:27648
	ds_write_b128 v245, v[144:147] offset:32256
	s_waitcnt lgkmcnt(0)
	s_barrier
	ds_read_b128 v[186:189], v240 offset:9216
	ds_read_b128 v[190:193], v240 offset:13824
	ds_read_b128 v[194:197], v240 offset:9248
	ds_read_b128 v[198:201], v240 offset:13856
	ds_read_b128 v[202:205], v240 offset:9280
	ds_read_b128 v[206:209], v240 offset:13888
	ds_read_b128 v[210:213], v240 offset:9312
	ds_read_b128 v[214:217], v240 offset:13920
	s_add_i32 s4, s39, 3
	s_cmp_ge_u32 s4, s38
	s_cbranch_scc1 .Lat_noload_b
	s_mov_b32 s4, 0x72e5000
	s_mov_b32 s5, 0
	s_mov_b32 s6, 0x731d000
	s_mov_b32 s7, 0
	v_lshl_add_u64 v[248:249], v[254:255], 0, s[4:5]
	v_lshl_add_u64 v[250:251], v[254:255], 0, s[6:7]
	global_load_dwordx4 v[132:135], v[248:249], off offset:1536
	global_load_dwordx4 v[140:143], v[248:249], off offset:2048
	global_load_dwordx4 v[136:139], v[250:251], off offset:1536
	global_load_dwordx4 v[144:147], v[250:251], off offset:2048
.Lat_noload_b:
	s_waitcnt vmcnt(8) lgkmcnt(0)
	v_mfma_f32_32x32x16_bf16 v[68:83], v[186:189], v[120:123], v[224:239]
	ds_read_b64_tr_b16 v[186:187], v241 offset:27648
	ds_read_b64_tr_b16 v[188:189], v241 offset:28800
	v_mfma_f32_32x32x16_bf16 v[84:99], v[190:193], v[120:123], v[224:239]
	ds_read_b64_tr_b16 v[190:191], v241 offset:27712
	ds_read_b64_tr_b16 v[192:193], v241 offset:28864
	v_mfma_f32_32x32x16_bf16 v[68:83], v[194:197], v[108:111], v[68:83]
	ds_read_b64_tr_b16 v[194:195], v241 offset:29952
	ds_read_b64_tr_b16 v[196:197], v241 offset:31104
	v_mfma_f32_32x32x16_bf16 v[84:99], v[198:201], v[108:111], v[84:99]
	ds_read_b64_tr_b16 v[198:199], v241 offset:30016
	ds_read_b64_tr_b16 v[200:201], v241 offset:31168
	v_mfma_f32_32x32x16_bf16 v[154:169], v[202:205], v[116:119], v[224:239]
	ds_read_b64_tr_b16 v[202:203], v242 offset:32256
	ds_read_b64_tr_b16 v[204:205], v242 offset:33408
	v_mfma_f32_32x32x16_bf16 v[170:185], v[206:209], v[116:119], v[224:239]
	ds_read_b64_tr_b16 v[206:207], v242 offset:32320
	ds_read_b64_tr_b16 v[208:209], v242 offset:33472
	v_mfma_f32_32x32x16_bf16 v[154:169], v[210:213], v[124:127], v[154:169]
	ds_read_b64_tr_b16 v[210:211], v242 offset:34560
	ds_read_b64_tr_b16 v[212:213], v242 offset:35712
	v_mfma_f32_32x32x16_bf16 v[170:185], v[214:217], v[124:127], v[170:185]
	ds_read_b64_tr_b16 v[214:215], v242 offset:34624
	ds_read_b64_tr_b16 v[216:217], v242 offset:35776
	v_exp_f32_e32 v68, v68
	v_exp_f32_e32 v69, v69
	v_exp_f32_e32 v70, v70
	v_exp_f32_e32 v71, v71
	v_exp_f32_e32 v72, v72
	v_exp_f32_e32 v73, v73
	v_exp_f32_e32 v74, v74
	v_exp_f32_e32 v75, v75
	v_pk_add_f32 v[220:221], v[68:69], v[220:221]
	v_pk_add_f32 v[220:221], v[70:71], v[220:221]
	v_pk_add_f32 v[220:221], v[72:73], v[220:221]
	v_pk_add_f32 v[220:221], v[74:75], v[220:221]
	v_cvt_pk_bf16_f32 v68, v68, v69
	v_cvt_pk_bf16_f32 v69, v70, v71
	v_cvt_pk_bf16_f32 v70, v72, v73
	v_cvt_pk_bf16_f32 v71, v74, v75
	s_waitcnt lgkmcnt(12)
	s_nop 0
	v_mfma_f32_32x32x16_bf16 v[4:19], v[186:189], v[68:71], v[4:19]
	v_mfma_f32_32x32x16_bf16 v[20:35], v[190:193], v[68:71], v[20:35]
	v_exp_f32_e32 v154, v154
	v_exp_f32_e32 v155, v155
	v_exp_f32_e32 v156, v156
	v_exp_f32_e32 v157, v157
	v_exp_f32_e32 v158, v158
	v_exp_f32_e32 v159, v159
	v_exp_f32_e32 v160, v160
	v_exp_f32_e32 v161, v161
	v_pk_add_f32 v[246:247], v[154:155], v[246:247]
	v_pk_add_f32 v[246:247], v[156:157], v[246:247]
	v_pk_add_f32 v[246:247], v[158:159], v[246:247]
	v_pk_add_f32 v[246:247], v[160:161], v[246:247]
	v_cvt_pk_bf16_f32 v154, v154, v155
	v_cvt_pk_bf16_f32 v155, v156, v157
	v_cvt_pk_bf16_f32 v156, v158, v159
	v_cvt_pk_bf16_f32 v157, v160, v161
	s_nop 1
	v_mfma_f32_32x32x16_bf16 v[36:51], v[186:189], v[154:157], v[36:51]
	v_mfma_f32_32x32x16_bf16 v[52:67], v[190:193], v[154:157], v[52:67]
	v_exp_f32_e32 v76, v76
	v_exp_f32_e32 v77, v77
	v_exp_f32_e32 v78, v78
	v_exp_f32_e32 v79, v79
	v_exp_f32_e32 v80, v80
	v_exp_f32_e32 v81, v81
	v_exp_f32_e32 v82, v82
	v_exp_f32_e32 v83, v83
	v_pk_add_f32 v[220:221], v[76:77], v[220:221]
	v_pk_add_f32 v[220:221], v[78:79], v[220:221]
	v_pk_add_f32 v[220:221], v[80:81], v[220:221]
	v_pk_add_f32 v[220:221], v[82:83], v[220:221]
	v_cvt_pk_bf16_f32 v76, v76, v77
	v_cvt_pk_bf16_f32 v77, v78, v79
	v_cvt_pk_bf16_f32 v78, v80, v81
	v_cvt_pk_bf16_f32 v79, v82, v83
	s_waitcnt lgkmcnt(8)
	s_nop 0
	v_mfma_f32_32x32x16_bf16 v[4:19], v[194:197], v[76:79], v[4:19]
	v_mfma_f32_32x32x16_bf16 v[20:35], v[198:201], v[76:79], v[20:35]
	v_exp_f32_e32 v162, v162
	v_exp_f32_e32 v163, v163
	v_exp_f32_e32 v164, v164
	v_exp_f32_e32 v165, v165
	v_exp_f32_e32 v166, v166
	v_exp_f32_e32 v167, v167
	v_exp_f32_e32 v168, v168
	v_exp_f32_e32 v169, v169
	v_pk_add_f32 v[246:247], v[162:163], v[246:247]
	v_pk_add_f32 v[246:247], v[164:165], v[246:247]
	v_pk_add_f32 v[246:247], v[166:167], v[246:247]
	v_pk_add_f32 v[246:247], v[168:169], v[246:247]
	v_cvt_pk_bf16_f32 v162, v162, v163
	v_cvt_pk_bf16_f32 v163, v164, v165
	v_cvt_pk_bf16_f32 v164, v166, v167
	v_cvt_pk_bf16_f32 v165, v168, v169
	s_nop 1
	v_mfma_f32_32x32x16_bf16 v[36:51], v[194:197], v[162:165], v[36:51]
	v_mfma_f32_32x32x16_bf16 v[52:67], v[198:201], v[162:165], v[52:67]
	v_exp_f32_e32 v84, v84
	v_exp_f32_e32 v85, v85
	v_exp_f32_e32 v86, v86
	v_exp_f32_e32 v87, v87
	v_exp_f32_e32 v88, v88
	v_exp_f32_e32 v89, v89
	v_exp_f32_e32 v90, v90
	v_exp_f32_e32 v91, v91
	v_pk_add_f32 v[220:221], v[84:85], v[220:221]
	v_pk_add_f32 v[220:221], v[86:87], v[220:221]
	v_pk_add_f32 v[220:221], v[88:89], v[220:221]
	v_pk_add_f32 v[220:221], v[90:91], v[220:221]
	v_cvt_pk_bf16_f32 v84, v84, v85
	v_cvt_pk_bf16_f32 v85, v86, v87
	v_cvt_pk_bf16_f32 v86, v88, v89
	v_cvt_pk_bf16_f32 v87, v90, v91
	s_waitcnt lgkmcnt(4)
	s_nop 0
	v_mfma_f32_32x32x16_bf16 v[4:19], v[202:205], v[84:87], v[4:19]
	v_mfma_f32_32x32x16_bf16 v[20:35], v[206:209], v[84:87], v[20:35]
	v_exp_f32_e32 v170, v170
	v_exp_f32_e32 v171, v171
	v_exp_f32_e32 v172, v172
	v_exp_f32_e32 v173, v173
	v_exp_f32_e32 v174, v174
	v_exp_f32_e32 v175, v175
	v_exp_f32_e32 v176, v176
	v_exp_f32_e32 v177, v177
	v_pk_add_f32 v[246:247], v[170:171], v[246:247]
	v_pk_add_f32 v[246:247], v[172:173], v[246:247]
	v_pk_add_f32 v[246:247], v[174:175], v[246:247]
	v_pk_add_f32 v[246:247], v[176:177], v[246:247]
	v_cvt_pk_bf16_f32 v170, v170, v171
	v_cvt_pk_bf16_f32 v171, v172, v173
	v_cvt_pk_bf16_f32 v172, v174, v175
	v_cvt_pk_bf16_f32 v173, v176, v177
	s_nop 1
	v_mfma_f32_32x32x16_bf16 v[36:51], v[202:205], v[170:173], v[36:51]
	v_mfma_f32_32x32x16_bf16 v[52:67], v[206:209], v[170:173], v[52:67]
	v_exp_f32_e32 v92, v92
	v_exp_f32_e32 v93, v93
	v_exp_f32_e32 v94, v94
	v_exp_f32_e32 v95, v95
	v_exp_f32_e32 v96, v96
	v_exp_f32_e32 v97, v97
	v_exp_f32_e32 v98, v98
	v_exp_f32_e32 v99, v99
	v_pk_add_f32 v[220:221], v[92:93], v[220:221]
	v_pk_add_f32 v[220:221], v[94:95], v[220:221]
	v_pk_add_f32 v[220:221], v[96:97], v[220:221]
	v_pk_add_f32 v[220:221], v[98:99], v[220:221]
	v_cvt_pk_bf16_f32 v92, v92, v93
	v_cvt_pk_bf16_f32 v93, v94, v95
	v_cvt_pk_bf16_f32 v94, v96, v97
	v_cvt_pk_bf16_f32 v95, v98, v99
	s_waitcnt lgkmcnt(0)
	s_nop 0
	v_mfma_f32_32x32x16_bf16 v[4:19], v[210:213], v[92:95], v[4:19]
	v_mfma_f32_32x32x16_bf16 v[20:35], v[214:217], v[92:95], v[20:35]
	v_exp_f32_e32 v178, v178
	v_exp_f32_e32 v179, v179
	v_exp_f32_e32 v180, v180
	v_exp_f32_e32 v181, v181
	v_exp_f32_e32 v182, v182
	v_exp_f32_e32 v183, v183
	v_exp_f32_e32 v184, v184
	v_exp_f32_e32 v185, v185
	v_pk_add_f32 v[246:247], v[178:179], v[246:247]
	v_pk_add_f32 v[246:247], v[180:181], v[246:247]
	v_pk_add_f32 v[246:247], v[182:183], v[246:247]
	v_pk_add_f32 v[246:247], v[184:185], v[246:247]
	v_cvt_pk_bf16_f32 v178, v178, v179
	v_cvt_pk_bf16_f32 v179, v180, v181
	v_cvt_pk_bf16_f32 v180, v182, v183
	v_cvt_pk_bf16_f32 v181, v184, v185
	s_nop 1
	v_mfma_f32_32x32x16_bf16 v[36:51], v[210:213], v[178:181], v[36:51]
	v_mfma_f32_32x32x16_bf16 v[52:67], v[214:217], v[178:181], v[52:67]
	v_max3_f32 v248, v220, v221, v246
	v_max_f32_e32 v248, v248, v247
	v_cmp_lt_f32_e32 vcc, 0x49800000, v248
	s_cbranch_vccz .Lat_norescale_b
	v_add_f32_e32 v250, v220, v221
	v_add_f32_e32 v251, v246, v247
	v_lshlrev_b32_e32 v249, 2, v222
	v_xor_b32_e32 v249, 0x80, v249
	v_and_b32_e32 v249, 0xfc, v249
	ds_bpermute_b32 v68, v249, v250
	ds_bpermute_b32 v69, v249, v251
	s_waitcnt lgkmcnt(0)
	v_add_f32_e32 v250, v250, v68
	v_add_f32_e32 v251, v251, v69
	v_max_f32_e32 v250, v250, v251
	v_log_f32_e32 v250, v250
	s_nop 0
	v_max_f32_e32 v250, 0, v250
	v_add_f32_e32 v244, v244, v250
	v_exp_f32_e64 v248, -v250
	v_xor_b32_e32 v224, 0x80000000, v244
	v_mov_b32_e32 v225, v224
	v_mov_b32_e32 v226, v224
	v_mov_b32_e32 v227, v224
	v_mov_b32_e32 v228, v224
	v_mov_b32_e32 v229, v224
	v_mov_b32_e32 v230, v224
	v_mov_b32_e32 v231, v224
	v_mov_b32_e32 v232, v224
	v_mov_b32_e32 v233, v224
	v_mov_b32_e32 v234, v224
	v_mov_b32_e32 v235, v224
	v_mov_b32_e32 v236, v224
	v_mov_b32_e32 v237, v224
	v_mov_b32_e32 v238, v224
	v_mov_b32_e32 v239, v224
	v_mul_f32_e32 v220, v220, v248
	v_mul_f32_e32 v221, v221, v248
	v_mul_f32_e32 v246, v246, v248
	v_mul_f32_e32 v247, v247, v248
	v_pk_mul_f32 v[4:5], v[4:5], v[248:249] op_sel_hi:[1,0]
	v_pk_mul_f32 v[6:7], v[6:7], v[248:249] op_sel_hi:[1,0]
	v_pk_mul_f32 v[8:9], v[8:9], v[248:249] op_sel_hi:[1,0]
	v_pk_mul_f32 v[10:11], v[10:11], v[248:249] op_sel_hi:[1,0]
	v_pk_mul_f32 v[12:13], v[12:13], v[248:249] op_sel_hi:[1,0]
	v_pk_mul_f32 v[14:15], v[14:15], v[248:249] op_sel_hi:[1,0]
	v_pk_mul_f32 v[16:17], v[16:17], v[248:249] op_sel_hi:[1,0]
	v_pk_mul_f32 v[18:19], v[18:19], v[248:249] op_sel_hi:[1,0]
	v_pk_mul_f32 v[20:21], v[20:21], v[248:249] op_sel_hi:[1,0]
	v_pk_mul_f32 v[22:23], v[22:23], v[248:249] op_sel_hi:[1,0]
	v_pk_mul_f32 v[24:25], v[24:25], v[248:249] op_sel_hi:[1,0]
	v_pk_mul_f32 v[26:27], v[26:27], v[248:249] op_sel_hi:[1,0]
	v_pk_mul_f32 v[28:29], v[28:29], v[248:249] op_sel_hi:[1,0]
	v_pk_mul_f32 v[30:31], v[30:31], v[248:249] op_sel_hi:[1,0]
	v_pk_mul_f32 v[32:33], v[32:33], v[248:249] op_sel_hi:[1,0]
	v_pk_mul_f32 v[34:35], v[34:35], v[248:249] op_sel_hi:[1,0]
	v_pk_mul_f32 v[36:37], v[36:37], v[248:249] op_sel_hi:[1,0]
	v_pk_mul_f32 v[38:39], v[38:39], v[248:249] op_sel_hi:[1,0]
	v_pk_mul_f32 v[40:41], v[40:41], v[248:249] op_sel_hi:[1,0]
	v_pk_mul_f32 v[42:43], v[42:43], v[248:249] op_sel_hi:[1,0]
	v_pk_mul_f32 v[44:45], v[44:45], v[248:249] op_sel_hi:[1,0]
	v_pk_mul_f32 v[46:47], v[46:47], v[248:249] op_sel_hi:[1,0]
	v_pk_mul_f32 v[48:49], v[48:49], v[248:249] op_sel_hi:[1,0]
	v_pk_mul_f32 v[50:51], v[50:51], v[248:249] op_sel_hi:[1,0]
	v_pk_mul_f32 v[52:53], v[52:53], v[248:249] op_sel_hi:[1,0]
	v_pk_mul_f32 v[54:55], v[54:55], v[248:249] op_sel_hi:[1,0]
	v_pk_mul_f32 v[56:57], v[56:57], v[248:249] op_sel_hi:[1,0]
	v_pk_mul_f32 v[58:59], v[58:59], v[248:249] op_sel_hi:[1,0]
	v_pk_mul_f32 v[60:61], v[60:61], v[248:249] op_sel_hi:[1,0]
	v_pk_mul_f32 v[62:63], v[62:63], v[248:249] op_sel_hi:[1,0]
	v_pk_mul_f32 v[64:65], v[64:65], v[248:249] op_sel_hi:[1,0]
	v_pk_mul_f32 v[66:67], v[66:67], v[248:249] op_sel_hi:[1,0]
